# seams 1 and 2 also row-panel barriers; W1d/W_in and the ACT-vs-QKV overwrite order kept by chip-wide arrival words
# speedup vs baseline: 1.0293x; 1.0067x over previous
; #define LAS __attribute__((address_space(3)))
; __device__ __forceinline__ unsigned xb_add(unsigned* p, unsigned v) { return __hip_atomic_fetch_add(p, v, __ATOMIC_RELAXED, __HIP_MEMORY_SCOPE_AGENT); }
; __device__ __forceinline__ unsigned xb_xcc_id() { return (unsigned)__builtin_amdgcn_s_getreg((3 << 11) | 20) & 0xFu; }
; __global__ void __launch_bounds__(NWAVES * 64, 2) mega_fwd(Args args) {
;     ...
;     int bx;
;     { volatile LAS unsigned* vb = (volatile LAS unsigned*)(lds + MISC_OFF + 96);
;       if (threadIdx.x == 0) { unsigned v = blockIdx.x;
;           if (G == 256) { const unsigned xcc = xb_xcc_id() & 7u; const unsigned slot = xb_add((unsigned*)(ws + WS_CTL) + 6144 + 64 * xcc, 1u); v = (slot & 31u) * 8u + xcc; }
;           vb[0] = v; }
;       __syncthreads(); bx = (int)__builtin_amdgcn_readfirstlane(vb[0]); __syncthreads(); }
;     const int vcu = (G % 8 == 0) ? (bx % 8) * (G / 8) + bx / 8 : bx;
_Z8mega_fwd4Args:
	s_mov_b32 s98, 0
	s_load_dwordx16 s[52:67], s[0:1], 0xc0
	s_load_dwordx4 s[84:87], s[0:1], 0x100
	s_load_dword s3, s[0:1], 0x110
	s_add_u32 s4, s0, 0x108
	s_addc_u32 s5, s1, 0
	v_cmp_eq_u32_e64 s[14:15], 0, v0
	s_waitcnt lgkmcnt(0)
	v_writelane_b32 v251, s3, 0
	s_and_saveexec_b64 s[6:7], s[14:15]
	s_cbranch_execz .LBB0_6
	s_cmpk_lg_i32 s86, 0x100
	v_mov_b32_e32 v1, s2
	s_cbranch_scc1 .LBB0_5
	s_mov_b64 s[2:3], exec
	v_mbcnt_lo_u32_b32 v1, s2, 0
	s_getreg_b32 s8, hwreg(HW_REG_XCC_ID, 0, 4)
	v_mbcnt_hi_u32_b32 v1, s3, v1
	s_and_b32 s10, s8, 7
	v_cmp_eq_u32_e32 vcc, 0, v1
	s_and_saveexec_b64 s[8:9], vcc
	s_cbranch_execz .LBB0_4
	s_lshl_b32 s11, s10, 8
	s_add_u32 s12, s66, s11
	s_addc_u32 s13, s67, 0
	s_bcnt1_i32_b64 s2, s[2:3]
	v_mov_b32_e32 v2, 0xfd06000
	v_mov_b32_e32 v3, s2
	global_atomic_add v2, v2, v3, s[12:13] sc0

; #define LAS __attribute__((address_space(3)))
; __device__ __forceinline__ unsigned pk2(float lo, float hi) { return f2bf(lo) | (f2bf(hi) << 16); }
; __device__ __forceinline__ void p0_transpose_item(const float* W, int K, int N, bf16* WT, const float* gain, int mode, LAS float* scr, int item, int lane) {
;     ...
;     const int c = lane & 7;
; #pragma unroll
;     for (int j = 0; j < 4; ++j) { const int n = (lane >> 3) + 8 * j; const LAS float* s = scr + (8 * c) * 33 + n;
;         v4u o; o.x = pk2(s[0 * 33], s[1 * 33]); o.y = pk2(s[2 * 33], s[3 * 33]); o.z = pk2(s[4 * 33], s[5 * 33]); o.w = pk2(s[6 * 33], s[7 * 33]);
;         const int ng = n0 + n; int row;
;         if (mode == 0) row = ng;
;         else if (mode == 3) {
;             if (ng < 512) row = (ng & ~255) + 128 * ((ng >> 5) & 1) + 32 * ((ng >> 6) & 3) + (ng & 31);
;             else if (ng < 640) row = 512 + 128 * ((ng >> 5) & 1) + 32 * ((ng >> 6) & 1) + (ng & 31);
;             else if (ng < 768) { const int vi = ng - 640; row = 512 + 128 * ((vi >> 5) & 1) + 32 * (2 + (vi >> 6)) + (vi & 31); }
;             else row = ng; }
;         else row = (ng >> 7) * 256 + (ng & 127) + (mode == 2 ? 128 : 0);
;         *(v4u*)(WT + (size_t)row * K + k0 + 8 * c) = o; }
.LBB0_192:
	s_waitcnt lgkmcnt(3)
	v_bfe_u32 v56, v42, 16, 1
	v_add3_u32 v42, v42, v56, s16
	v_bfe_u32 v56, v43, 16, 1
	v_lshrrev_b32_e32 v42, 16, v42
	v_add3_u32 v43, v43, v56, s16
	v_and_or_b32 v108, v43, s17, v42
	s_waitcnt lgkmcnt(2)
	v_bfe_u32 v42, v40, 16, 1
	v_add3_u32 v40, v40, v42, s16
	v_bfe_u32 v42, v41, 16, 1
	v_lshrrev_b32_e32 v40, 16, v40
	v_add3_u32 v41, v41, v42, s16
	v_and_or_b32 v109, v41, s17, v40
	s_waitcnt lgkmcnt(1)
	v_bfe_u32 v40, v38, 16, 1
	v_add3_u32 v38, v38, v40, s16
	v_bfe_u32 v40, v39, 16, 1
	v_lshrrev_b32_e32 v38, 16, v38
	v_add3_u32 v39, v39, v40, s16
	v_and_or_b32 v110, v39, s17, v38
	s_waitcnt lgkmcnt(0)
	v_bfe_u32 v38, v36, 16, 1
	v_add3_u32 v36, v36, v38, s16
	v_bfe_u32 v38, v37, 16, 1
	s_lshl_b32 s10, s23, 1
	v_lshrrev_b32_e32 v36, 16, v36
	v_add3_u32 v37, v37, v38, s16
	v_lshl_add_u64 v[34:35], v[70:71], 0, s[10:11]
	v_and_or_b32 v111, v37, s17, v36
	v_lshlrev_b64 v[36:37], 11, v[66:67]
	v_lshl_add_u64 v[36:37], v[34:35], 0, v[36:37]
	global_store_dwordx4 v[36:37], v[108:111], off sc1
	ds_read2_b32 v[42:43], v97 offset0:8 offset1:41
	ds_read2_b32 v[40:41], v97 offset0:74 offset1:107
	ds_read2_b32 v[38:39], v97 offset0:140 offset1:173
	ds_read2_b32 v[36:37], v97 offset0:206 offset1:239
	v_cndmask_b32_e64 v56, 0, 1, s[12:13]
	v_cmp_ne_u32_e64 s[4:5], 1, v56
	s_andn2_b64 vcc, exec, s[12:13]
	s_mov_b64 s[12:13], -1
	s_cbranch_vccnz .LBB0_198
	s_cmp_lt_u32 s18, 10
	s_cbranch_scc1 .LBB0_195
	s_cmp_lt_u32 s18, 12
	s_cselect_b64 vcc, -1, 0
	s_add_i32 s10, s19, 0xfffffd80
	s_lshr_b32 s10, s10, 1
	v_or_b32_e32 v56, s19, v94
	v_add_u32_e32 v57, s10, v99
	v_cndmask_b32_e32 v66, v56, v57, vcc
	s_mov_b64 s[12:13], 0

; #define LAS __attribute__((address_space(3)))
; __device__ __forceinline__ unsigned pk2(float lo, float hi) { return f2bf(lo) | (f2bf(hi) << 16); }
; __device__ __forceinline__ void p0_transpose_item(const float* W, int K, int N, bf16* WT, const float* gain, int mode, LAS float* scr, int item, int lane) {
;     ...
;     const int c = lane & 7;
; #pragma unroll
;     for (int j = 0; j < 4; ++j) { const int n = (lane >> 3) + 8 * j; const LAS float* s = scr + (8 * c) * 33 + n;
;         v4u o; o.x = pk2(s[0 * 33], s[1 * 33]); o.y = pk2(s[2 * 33], s[3 * 33]); o.z = pk2(s[4 * 33], s[5 * 33]); o.w = pk2(s[6 * 33], s[7 * 33]);
;         const int ng = n0 + n; int row;
;         if (mode == 0) row = ng;
;         else if (mode == 3) {
;             if (ng < 512) row = (ng & ~255) + 128 * ((ng >> 5) & 1) + 32 * ((ng >> 6) & 3) + (ng & 31);
;             else if (ng < 640) row = 512 + 128 * ((ng >> 5) & 1) + 32 * ((ng >> 6) & 1) + (ng & 31);
;             else if (ng < 768) { const int vi = ng - 640; row = 512 + 128 * ((vi >> 5) & 1) + 32 * (2 + (vi >> 6)) + (vi & 31); }
;             else row = ng; }
;         else row = (ng >> 7) * 256 + (ng & 127) + (mode == 2 ? 128 : 0);
;         *(v4u*)(WT + (size_t)row * K + k0 + 8 * c) = o; }
.LBB0_200:
	s_waitcnt lgkmcnt(3)
	v_bfe_u32 v56, v42, 16, 1
	v_add3_u32 v42, v42, v56, s16
	v_bfe_u32 v56, v43, 16, 1
	v_lshrrev_b32_e32 v42, 16, v42
	v_add3_u32 v43, v43, v56, s16
	v_and_or_b32 v108, v43, s17, v42
	s_waitcnt lgkmcnt(2)
	v_bfe_u32 v42, v40, 16, 1
	v_add3_u32 v40, v40, v42, s16
	v_bfe_u32 v42, v41, 16, 1
	v_lshrrev_b32_e32 v40, 16, v40
	v_add3_u32 v41, v41, v42, s16
	v_and_or_b32 v109, v41, s17, v40
	s_waitcnt lgkmcnt(1)
	v_bfe_u32 v40, v38, 16, 1
	v_add3_u32 v38, v38, v40, s16
	v_bfe_u32 v40, v39, 16, 1
	v_lshrrev_b32_e32 v38, 16, v38
	v_add3_u32 v39, v39, v40, s16
	v_and_or_b32 v110, v39, s17, v38
	s_waitcnt lgkmcnt(0)
	v_bfe_u32 v38, v36, 16, 1
	v_add3_u32 v36, v36, v38, s16
	v_bfe_u32 v38, v37, 16, 1
	v_lshrrev_b32_e32 v36, 16, v36
	v_add3_u32 v37, v37, v38, s16
	v_and_or_b32 v111, v37, s17, v36
	ds_read2_b32 v[42:43], v97 offset0:16 offset1:49
	ds_read2_b32 v[40:41], v97 offset0:82 offset1:115
	ds_read2_b32 v[38:39], v97 offset0:148 offset1:181
	ds_read2_b32 v[36:37], v97 offset0:214 offset1:247
	v_lshlrev_b64 v[56:57], 11, v[66:67]
	v_lshl_add_u64 v[56:57], v[34:35], 0, v[56:57]
	s_and_b64 vcc, exec, s[4:5]
	s_mov_b64 s[12:13], -1
	global_store_dwordx4 v[56:57], v[108:111], off sc1
	s_cbranch_vccnz .LBB0_206
	s_cmp_lt_u32 s18, 10
	s_cbranch_scc1 .LBB0_203
	s_cmp_lt_u32 s18, 12
	s_cselect_b64 vcc, -1, 0
	s_add_i32 s10, s19, 0xfffffd80
	s_lshr_b32 s10, s10, 1
	v_or_b32_e32 v56, s19, v95
	v_add_u32_e32 v57, s10, v100
	v_cndmask_b32_e32 v66, v56, v57, vcc
	s_mov_b64 s[12:13], 0

; #define LAS __attribute__((address_space(3)))
; __device__ __forceinline__ unsigned pk2(float lo, float hi) { return f2bf(lo) | (f2bf(hi) << 16); }
; __device__ __forceinline__ void p0_transpose_item(const float* W, int K, int N, bf16* WT, const float* gain, int mode, LAS float* scr, int item, int lane) {
;     ...
;     const int c = lane & 7;
; #pragma unroll
;     for (int j = 0; j < 4; ++j) { const int n = (lane >> 3) + 8 * j; const LAS float* s = scr + (8 * c) * 33 + n;
;         v4u o; o.x = pk2(s[0 * 33], s[1 * 33]); o.y = pk2(s[2 * 33], s[3 * 33]); o.z = pk2(s[4 * 33], s[5 * 33]); o.w = pk2(s[6 * 33], s[7 * 33]);
;         const int ng = n0 + n; int row;
;         if (mode == 0) row = ng;
;         else if (mode == 3) {
;             if (ng < 512) row = (ng & ~255) + 128 * ((ng >> 5) & 1) + 32 * ((ng >> 6) & 3) + (ng & 31);
;             else if (ng < 640) row = 512 + 128 * ((ng >> 5) & 1) + 32 * ((ng >> 6) & 1) + (ng & 31);
;             else if (ng < 768) { const int vi = ng - 640; row = 512 + 128 * ((vi >> 5) & 1) + 32 * (2 + (vi >> 6)) + (vi & 31); }
;             else row = ng; }
;         else row = (ng >> 7) * 256 + (ng & 127) + (mode == 2 ? 128 : 0);
;         *(v4u*)(WT + (size_t)row * K + k0 + 8 * c) = o; }
.LBB0_208:
	s_waitcnt lgkmcnt(3)
	v_bfe_u32 v56, v42, 16, 1
	v_add3_u32 v42, v42, v56, s16
	v_bfe_u32 v56, v43, 16, 1
	v_lshrrev_b32_e32 v42, 16, v42
	v_add3_u32 v43, v43, v56, s16
	v_and_or_b32 v108, v43, s17, v42
	s_waitcnt lgkmcnt(2)
	v_bfe_u32 v42, v40, 16, 1
	v_add3_u32 v40, v40, v42, s16
	v_bfe_u32 v42, v41, 16, 1
	v_lshrrev_b32_e32 v40, 16, v40
	v_add3_u32 v41, v41, v42, s16
	v_and_or_b32 v109, v41, s17, v40
	s_waitcnt lgkmcnt(1)
	v_bfe_u32 v40, v38, 16, 1
	v_add3_u32 v38, v38, v40, s16
	v_bfe_u32 v40, v39, 16, 1
	v_lshrrev_b32_e32 v38, 16, v38
	v_add3_u32 v39, v39, v40, s16
	v_and_or_b32 v110, v39, s17, v38
	s_waitcnt lgkmcnt(0)
	v_bfe_u32 v38, v36, 16, 1
	v_add3_u32 v36, v36, v38, s16
	v_bfe_u32 v38, v37, 16, 1
	v_lshrrev_b32_e32 v36, 16, v36
	v_add3_u32 v37, v37, v38, s16
	v_and_or_b32 v111, v37, s17, v36
	ds_read2_b32 v[42:43], v97 offset0:24 offset1:57
	ds_read2_b32 v[40:41], v97 offset0:90 offset1:123
	ds_read2_b32 v[38:39], v97 offset0:156 offset1:189
	ds_read2_b32 v[36:37], v97 offset0:222 offset1:255
	v_lshlrev_b64 v[56:57], 11, v[66:67]
	v_lshl_add_u64 v[56:57], v[34:35], 0, v[56:57]
	s_and_b64 vcc, exec, s[4:5]
	s_mov_b64 s[12:13], -1
	global_store_dwordx4 v[56:57], v[108:111], off sc1
	s_cbranch_vccnz .LBB0_214
	s_cmp_lt_u32 s18, 10
	s_cbranch_scc1 .LBB0_211
	s_cmp_lt_u32 s18, 12
	s_cselect_b64 vcc, -1, 0
	s_add_i32 s10, s19, 0xfffffd80
	s_lshr_b32 s10, s10, 1
	v_or_b32_e32 v56, s19, v96
	v_add_u32_e32 v57, s10, v101
	v_cndmask_b32_e32 v66, v56, v57, vcc
	s_mov_b64 s[12:13], 0

; #define LAS __attribute__((address_space(3)))
; #define LDS_WAIT() asm volatile("s_waitcnt lgkmcnt(0)" ::: "memory")
; __device__ __forceinline__ unsigned pk2(float lo, float hi) { return f2bf(lo) | (f2bf(hi) << 16); }
; __device__ __forceinline__ void p0_transpose_item(const float* W, int K, int N, bf16* WT, const float* gain, int mode, LAS float* scr, int item, int lane) {
;     ...
;     for (int hf = 0; hf < 2; ++hf) { const int n0 = n00 + 32 * hf;
; #pragma unroll
;       for (int i = 0; i < 8; ++i) { const int kk = (lane >> 3) + 8 * i; LAS float* d = scr + kk * 33 + 4 * (lane & 7);
;           d[0] = w[hf][i].x * gn[i]; d[1] = w[hf][i].y * gn[i]; d[2] = w[hf][i].z * gn[i]; d[3] = w[hf][i].w * gn[i]; }
;     LDS_WAIT(); asm volatile("" ::: "memory");
;     const int c = lane & 7;
; #pragma unroll
;     for (int j = 0; j < 4; ++j) { const int n = (lane >> 3) + 8 * j; const LAS float* s = scr + (8 * c) * 33 + n;
;         v4u o; o.x = pk2(s[0 * 33], s[1 * 33]); o.y = pk2(s[2 * 33], s[3 * 33]); o.z = pk2(s[4 * 33], s[5 * 33]); o.w = pk2(s[6 * 33], s[7 * 33]);
;         const int ng = n0 + n; int row;
;         if (mode == 0) row = ng;
;         else if (mode == 3) {
;             if (ng < 512) row = (ng & ~255) + 128 * ((ng >> 5) & 1) + 32 * ((ng >> 6) & 3) + (ng & 31);
;             else if (ng < 640) row = 512 + 128 * ((ng >> 5) & 1) + 32 * ((ng >> 6) & 1) + (ng & 31);
;             else if (ng < 768) { const int vi = ng - 640; row = 512 + 128 * ((vi >> 5) & 1) + 32 * (2 + (vi >> 6)) + (vi & 31); }
;             else row = ng; }
;         else row = (ng >> 7) * 256 + (ng & 127) + (mode == 2 ? 128 : 0);
;         *(v4u*)(WT + (size_t)row * K + k0 + 8 * c) = o; }
.LBB0_216:
	s_waitcnt lgkmcnt(3)
	v_bfe_u32 v56, v42, 16, 1
	v_add3_u32 v42, v42, v56, s16
	v_bfe_u32 v56, v43, 16, 1
	v_lshrrev_b32_e32 v42, 16, v42
	v_add3_u32 v43, v43, v56, s16
	v_and_or_b32 v108, v43, s17, v42
	s_waitcnt lgkmcnt(2)
	v_bfe_u32 v42, v40, 16, 1
	v_add3_u32 v40, v40, v42, s16
	v_bfe_u32 v42, v41, 16, 1
	v_lshrrev_b32_e32 v40, 16, v40
	v_add3_u32 v41, v41, v42, s16
	v_and_or_b32 v109, v41, s17, v40
	s_waitcnt lgkmcnt(1)
	v_bfe_u32 v40, v38, 16, 1
	v_add3_u32 v38, v38, v40, s16
	v_bfe_u32 v40, v39, 16, 1
	v_lshrrev_b32_e32 v38, 16, v38
	v_add3_u32 v39, v39, v40, s16
	v_and_or_b32 v110, v39, s17, v38
	s_waitcnt lgkmcnt(0)
	v_bfe_u32 v38, v36, 16, 1
	v_add3_u32 v36, v36, v38, s16
	v_bfe_u32 v38, v37, 16, 1
	v_lshrrev_b32_e32 v36, 16, v36
	v_add3_u32 v37, v37, v38, s16
	v_and_or_b32 v111, v37, s17, v36
	v_lshlrev_b64 v[36:37], 11, v[66:67]
	v_lshl_add_u64 v[36:37], v[34:35], 0, v[36:37]
	v_mov_b32_e32 v81, v80
	v_mov_b32_e32 v77, v76
	v_mov_b32_e32 v85, v84
	v_mov_b32_e32 v79, v78
	v_mov_b32_e32 v89, v88
	v_mov_b32_e32 v83, v82
	v_mov_b32_e32 v91, v90
	v_mov_b32_e32 v87, v86
	global_store_dwordx4 v[36:37], v[108:111], off sc1
	s_waitcnt lgkmcnt(0)
	v_pk_mul_f32 v[30:31], v[30:31], v[80:81]
	v_pk_mul_f32 v[26:27], v[26:27], v[76:77]
	v_pk_mul_f32 v[22:23], v[22:23], v[84:85]
	v_pk_mul_f32 v[18:19], v[18:19], v[78:79]
	v_pk_mul_f32 v[14:15], v[14:15], v[88:89]
	v_pk_mul_f32 v[10:11], v[10:11], v[82:83]
	v_pk_mul_f32 v[6:7], v[6:7], v[90:91]
	v_pk_mul_f32 v[2:3], v[2:3], v[86:87]
	ds_write2_b32 v62, v30, v31 offset1:1
	v_pk_mul_f32 v[30:31], v[32:33], v[80:81]
	ds_write2_b32 v58, v26, v27 offset1:1
	v_pk_mul_f32 v[26:27], v[28:29], v[76:77]
	ds_write2_b32 v54, v22, v23 offset1:1
	v_pk_mul_f32 v[22:23], v[24:25], v[84:85]
	ds_write2_b32 v50, v18, v19 offset1:1
	v_pk_mul_f32 v[18:19], v[20:21], v[78:79]
	ds_write2_b32 v46, v14, v15 offset1:1
	v_pk_mul_f32 v[14:15], v[16:17], v[88:89]
	ds_write2_b32 v48, v10, v11 offset1:1
	v_pk_mul_f32 v[10:11], v[12:13], v[82:83]
	ds_write2_b32 v45, v6, v7 offset1:1
	v_pk_mul_f32 v[6:7], v[8:9], v[90:91]
	ds_write2_b32 v52, v2, v3 offset1:1
	v_pk_mul_f32 v[2:3], v[4:5], v[86:87]
	ds_write2_b32 v62, v30, v31 offset0:2 offset1:3
	ds_write2_b32 v59, v26, v27 offset1:1
	ds_write2_b32 v55, v22, v23 offset1:1
	ds_write2_b32 v51, v18, v19 offset1:1
	ds_write2_b32 v47, v14, v15 offset1:1
	ds_write2_b32 v44, v10, v11 offset1:1
	ds_write2_b32 v49, v6, v7 offset1:1
	ds_write2_b32 v53, v2, v3 offset1:1
	s_waitcnt lgkmcnt(0)
	ds_read2_b32 v[8:9], v97 offset1:33
	ds_read2_b32 v[6:7], v97 offset0:66 offset1:99
	ds_read2_b32 v[4:5], v97 offset0:132 offset1:165
	ds_read2_b32 v[2:3], v97 offset0:198 offset1:231
	s_or_b32 s22, s19, 32
	s_or_b32 s10, s20, 0x280
	s_and_b64 vcc, exec, s[4:5]
	s_mov_b64 s[12:13], -1
	s_cbranch_vccnz .LBB0_222
	s_cmp_lt_u32 s18, 10
	s_cbranch_scc1 .LBB0_219
	s_cmp_lt_u32 s18, 12
	s_cselect_b64 vcc, -1, 0
	s_add_i32 s12, s19, 0xfffffda0
	s_lshr_b32 s12, s12, 1
	s_and_b32 s12, s12, 0x7fffffe0
	v_or_b32_e32 v10, s22, v1
	v_add_u32_e32 v11, s12, v102
	v_cndmask_b32_e32 v66, v10, v11, vcc
	s_mov_b64 s[12:13], 0

; #define LAS __attribute__((address_space(3)))
; __device__ __forceinline__ unsigned pk2(float lo, float hi) { return f2bf(lo) | (f2bf(hi) << 16); }
; __device__ __forceinline__ void p0_transpose_item(const float* W, int K, int N, bf16* WT, const float* gain, int mode, LAS float* scr, int item, int lane) {
;     ...
;     const int c = lane & 7;
; #pragma unroll
;     for (int j = 0; j < 4; ++j) { const int n = (lane >> 3) + 8 * j; const LAS float* s = scr + (8 * c) * 33 + n;
;         v4u o; o.x = pk2(s[0 * 33], s[1 * 33]); o.y = pk2(s[2 * 33], s[3 * 33]); o.z = pk2(s[4 * 33], s[5 * 33]); o.w = pk2(s[6 * 33], s[7 * 33]);
;         const int ng = n0 + n; int row;
;         if (mode == 0) row = ng;
;         else if (mode == 3) {
;             if (ng < 512) row = (ng & ~255) + 128 * ((ng >> 5) & 1) + 32 * ((ng >> 6) & 3) + (ng & 31);
;             else if (ng < 640) row = 512 + 128 * ((ng >> 5) & 1) + 32 * ((ng >> 6) & 1) + (ng & 31);
;             else if (ng < 768) { const int vi = ng - 640; row = 512 + 128 * ((vi >> 5) & 1) + 32 * (2 + (vi >> 6)) + (vi & 31); }
;             else row = ng; }
;         else row = (ng >> 7) * 256 + (ng & 127) + (mode == 2 ? 128 : 0);
;         *(v4u*)(WT + (size_t)row * K + k0 + 8 * c) = o; }
.LBB0_224:
	s_waitcnt lgkmcnt(3)
	v_bfe_u32 v10, v8, 16, 1
	v_add3_u32 v8, v8, v10, s16
	v_bfe_u32 v10, v9, 16, 1
	v_lshrrev_b32_e32 v8, 16, v8
	v_add3_u32 v9, v9, v10, s16
	v_and_or_b32 v10, v9, s17, v8
	s_waitcnt lgkmcnt(2)
	v_bfe_u32 v8, v6, 16, 1
	v_add3_u32 v6, v6, v8, s16
	v_bfe_u32 v8, v7, 16, 1
	v_lshrrev_b32_e32 v6, 16, v6
	v_add3_u32 v7, v7, v8, s16
	v_and_or_b32 v11, v7, s17, v6
	s_waitcnt lgkmcnt(1)
	v_bfe_u32 v6, v4, 16, 1
	v_add3_u32 v4, v4, v6, s16
	v_bfe_u32 v6, v5, 16, 1
	v_lshrrev_b32_e32 v4, 16, v4
	v_add3_u32 v5, v5, v6, s16
	v_and_or_b32 v12, v5, s17, v4
	s_waitcnt lgkmcnt(0)
	v_bfe_u32 v4, v2, 16, 1
	v_add3_u32 v2, v2, v4, s16
	v_bfe_u32 v4, v3, 16, 1
	v_lshrrev_b32_e32 v2, 16, v2
	v_add3_u32 v3, v3, v4, s16
	v_and_or_b32 v13, v3, s17, v2
	ds_read2_b32 v[8:9], v97 offset0:8 offset1:41
	ds_read2_b32 v[6:7], v97 offset0:74 offset1:107
	ds_read2_b32 v[4:5], v97 offset0:140 offset1:173
	ds_read2_b32 v[2:3], v97 offset0:206 offset1:239
	v_lshlrev_b64 v[14:15], 11, v[66:67]
	v_lshl_add_u64 v[14:15], v[34:35], 0, v[14:15]
	s_and_b64 vcc, exec, s[4:5]
	s_mov_b64 s[12:13], -1
	global_store_dwordx4 v[14:15], v[10:13], off sc1
	s_cbranch_vccnz .LBB0_230
	s_cmp_lt_u32 s18, 10
	s_cbranch_scc1 .LBB0_227
	s_cmp_lt_u32 s18, 12
	s_cselect_b64 vcc, -1, 0
	s_add_i32 s12, s19, 0xfffffda0
	s_lshr_b32 s12, s12, 1
	s_and_b32 s12, s12, 0x7fffffe0
	v_or_b32_e32 v10, s22, v94
	v_add_u32_e32 v11, s12, v103
	v_cndmask_b32_e32 v66, v10, v11, vcc
	s_mov_b64 s[12:13], 0

; #define LAS __attribute__((address_space(3)))
; __device__ __forceinline__ unsigned pk2(float lo, float hi) { return f2bf(lo) | (f2bf(hi) << 16); }
; __device__ __forceinline__ void p0_transpose_item(const float* W, int K, int N, bf16* WT, const float* gain, int mode, LAS float* scr, int item, int lane) {
;     ...
;     const int c = lane & 7;
; #pragma unroll
;     for (int j = 0; j < 4; ++j) { const int n = (lane >> 3) + 8 * j; const LAS float* s = scr + (8 * c) * 33 + n;
;         v4u o; o.x = pk2(s[0 * 33], s[1 * 33]); o.y = pk2(s[2 * 33], s[3 * 33]); o.z = pk2(s[4 * 33], s[5 * 33]); o.w = pk2(s[6 * 33], s[7 * 33]);
;         const int ng = n0 + n; int row;
;         if (mode == 0) row = ng;
;         else if (mode == 3) {
;             if (ng < 512) row = (ng & ~255) + 128 * ((ng >> 5) & 1) + 32 * ((ng >> 6) & 3) + (ng & 31);
;             else if (ng < 640) row = 512 + 128 * ((ng >> 5) & 1) + 32 * ((ng >> 6) & 1) + (ng & 31);
;             else if (ng < 768) { const int vi = ng - 640; row = 512 + 128 * ((vi >> 5) & 1) + 32 * (2 + (vi >> 6)) + (vi & 31); }
;             else row = ng; }
;         else row = (ng >> 7) * 256 + (ng & 127) + (mode == 2 ? 128 : 0);
;         *(v4u*)(WT + (size_t)row * K + k0 + 8 * c) = o; }
.LBB0_232:
	s_waitcnt lgkmcnt(3)
	v_bfe_u32 v10, v8, 16, 1
	v_add3_u32 v8, v8, v10, s16
	v_bfe_u32 v10, v9, 16, 1
	v_lshrrev_b32_e32 v8, 16, v8
	v_add3_u32 v9, v9, v10, s16
	v_and_or_b32 v10, v9, s17, v8
	s_waitcnt lgkmcnt(2)
	v_bfe_u32 v8, v6, 16, 1
	v_add3_u32 v6, v6, v8, s16
	v_bfe_u32 v8, v7, 16, 1
	v_lshrrev_b32_e32 v6, 16, v6
	v_add3_u32 v7, v7, v8, s16
	v_and_or_b32 v11, v7, s17, v6
	s_waitcnt lgkmcnt(1)
	v_bfe_u32 v6, v4, 16, 1
	v_add3_u32 v4, v4, v6, s16
	v_bfe_u32 v6, v5, 16, 1
	v_lshrrev_b32_e32 v4, 16, v4
	v_add3_u32 v5, v5, v6, s16
	v_and_or_b32 v12, v5, s17, v4
	s_waitcnt lgkmcnt(0)
	v_bfe_u32 v4, v2, 16, 1
	v_add3_u32 v2, v2, v4, s16
	v_bfe_u32 v4, v3, 16, 1
	v_lshrrev_b32_e32 v2, 16, v2
	v_add3_u32 v3, v3, v4, s16
	v_and_or_b32 v13, v3, s17, v2
	ds_read2_b32 v[8:9], v97 offset0:16 offset1:49
	ds_read2_b32 v[6:7], v97 offset0:82 offset1:115
	ds_read2_b32 v[4:5], v97 offset0:148 offset1:181
	ds_read2_b32 v[2:3], v97 offset0:214 offset1:247
	v_lshlrev_b64 v[14:15], 11, v[66:67]
	v_lshl_add_u64 v[14:15], v[34:35], 0, v[14:15]
	s_and_b64 vcc, exec, s[4:5]
	s_mov_b64 s[12:13], -1
	global_store_dwordx4 v[14:15], v[10:13], off sc1
	s_cbranch_vccnz .LBB0_238
	s_cmp_lt_u32 s18, 10
	s_cbranch_scc1 .LBB0_235
	s_cmp_lt_u32 s18, 12
	s_cselect_b64 vcc, -1, 0
	s_add_i32 s12, s19, 0xfffffda0
	s_lshr_b32 s12, s12, 1
	s_and_b32 s12, s12, 0x7fffffe0
	v_or_b32_e32 v10, s22, v95
	v_add_u32_e32 v11, s12, v104
	v_cndmask_b32_e32 v66, v10, v11, vcc
	s_mov_b64 s[12:13], 0

; #define LAS __attribute__((address_space(3)))
; __device__ __forceinline__ unsigned pk2(float lo, float hi) { return f2bf(lo) | (f2bf(hi) << 16); }
; __device__ __forceinline__ void p0_transpose_item(const float* W, int K, int N, bf16* WT, const float* gain, int mode, LAS float* scr, int item, int lane) {
;     ...
;     const int c = lane & 7;
; #pragma unroll
;     for (int j = 0; j < 4; ++j) { const int n = (lane >> 3) + 8 * j; const LAS float* s = scr + (8 * c) * 33 + n;
;         v4u o; o.x = pk2(s[0 * 33], s[1 * 33]); o.y = pk2(s[2 * 33], s[3 * 33]); o.z = pk2(s[4 * 33], s[5 * 33]); o.w = pk2(s[6 * 33], s[7 * 33]);
;         const int ng = n0 + n; int row;
;         if (mode == 0) row = ng;
;         else if (mode == 3) {
;             if (ng < 512) row = (ng & ~255) + 128 * ((ng >> 5) & 1) + 32 * ((ng >> 6) & 3) + (ng & 31);
;             else if (ng < 640) row = 512 + 128 * ((ng >> 5) & 1) + 32 * ((ng >> 6) & 1) + (ng & 31);
;             else if (ng < 768) { const int vi = ng - 640; row = 512 + 128 * ((vi >> 5) & 1) + 32 * (2 + (vi >> 6)) + (vi & 31); }
;             else row = ng; }
;         else row = (ng >> 7) * 256 + (ng & 127) + (mode == 2 ? 128 : 0);
;         *(v4u*)(WT + (size_t)row * K + k0 + 8 * c) = o; }
.LBB0_240:
	s_waitcnt lgkmcnt(3)
	v_bfe_u32 v10, v8, 16, 1
	v_add3_u32 v8, v8, v10, s16
	v_bfe_u32 v10, v9, 16, 1
	v_lshrrev_b32_e32 v8, 16, v8
	v_add3_u32 v9, v9, v10, s16
	v_and_or_b32 v10, v9, s17, v8
	s_waitcnt lgkmcnt(2)
	v_bfe_u32 v8, v6, 16, 1
	v_add3_u32 v6, v6, v8, s16
	v_bfe_u32 v8, v7, 16, 1
	v_lshrrev_b32_e32 v6, 16, v6
	v_add3_u32 v7, v7, v8, s16
	v_and_or_b32 v11, v7, s17, v6
	s_waitcnt lgkmcnt(1)
	v_bfe_u32 v6, v4, 16, 1
	v_add3_u32 v4, v4, v6, s16
	v_bfe_u32 v6, v5, 16, 1
	v_lshrrev_b32_e32 v4, 16, v4
	v_add3_u32 v5, v5, v6, s16
	v_and_or_b32 v12, v5, s17, v4
	s_waitcnt lgkmcnt(0)
	v_bfe_u32 v4, v2, 16, 1
	v_add3_u32 v2, v2, v4, s16
	v_bfe_u32 v4, v3, 16, 1
	v_lshrrev_b32_e32 v2, 16, v2
	v_add3_u32 v3, v3, v4, s16
	v_and_or_b32 v13, v3, s17, v2
	ds_read2_b32 v[8:9], v97 offset0:24 offset1:57
	ds_read2_b32 v[6:7], v97 offset0:90 offset1:123
	ds_read2_b32 v[4:5], v97 offset0:156 offset1:189
	ds_read2_b32 v[2:3], v97 offset0:222 offset1:255
	v_lshlrev_b64 v[14:15], 11, v[66:67]
	v_lshl_add_u64 v[14:15], v[34:35], 0, v[14:15]
	s_and_b64 vcc, exec, s[4:5]
	s_mov_b64 s[4:5], -1
	global_store_dwordx4 v[14:15], v[10:13], off sc1
	s_cbranch_vccnz .LBB0_246
	s_cmp_lt_u32 s18, 10
	s_cbranch_scc1 .LBB0_243
	s_cmp_lt_u32 s18, 12
	s_cselect_b64 vcc, -1, 0
	s_addk_i32 s19, 0xfda0
	s_lshr_b32 s4, s19, 1
	s_and_b32 s4, s4, 0x7fffffe0
	v_or_b32_e32 v10, s22, v96
	v_add_u32_e32 v11, s4, v105
	v_cndmask_b32_e32 v66, v10, v11, vcc
	s_mov_b64 s[4:5], 0

; #define LAS __attribute__((address_space(3)))
; #define LDS_WAIT() asm volatile("s_waitcnt lgkmcnt(0)" ::: "memory")
; __device__ __forceinline__ unsigned pk2(float lo, float hi) { return f2bf(lo) | (f2bf(hi) << 16); }
; __device__ __forceinline__ void p0_transpose_item(const float* W, int K, int N, bf16* WT, const float* gain, int mode, LAS float* scr, int item, int lane) {
;     ...
;         for (int i = 0; i < 8; ++i) w[hf][i] = __builtin_nontemporal_load((const f32x4*)(W + (size_t)(k0 + (lane >> 3) + 8 * i) * N + n00 + 32 * hf + 4 * (lane & 7)));
; #pragma unroll
;     for (int i = 0; i < 8; ++i) gn[i] = gain ? gain[k0 + (lane >> 3) + 8 * i] : 1.0f;
; #pragma unroll
;     for (int hf = 0; hf < 2; ++hf) { const int n0 = n00 + 32 * hf;
; #pragma unroll
;       for (int i = 0; i < 8; ++i) { const int kk = (lane >> 3) + 8 * i; LAS float* d = scr + kk * 33 + 4 * (lane & 7);
;           d[0] = w[hf][i].x * gn[i]; d[1] = w[hf][i].y * gn[i]; d[2] = w[hf][i].z * gn[i]; d[3] = w[hf][i].w * gn[i]; }
;     LDS_WAIT(); asm volatile("" ::: "memory");
;     const int c = lane & 7;
; #pragma unroll
;     for (int j = 0; j < 4; ++j) { const int n = (lane >> 3) + 8 * j; const LAS float* s = scr + (8 * c) * 33 + n;
;         v4u o; o.x = pk2(s[0 * 33], s[1 * 33]); o.y = pk2(s[2 * 33], s[3 * 33]); o.z = pk2(s[4 * 33], s[5 * 33]); o.w = pk2(s[6 * 33], s[7 * 33]);
;         const int ng = n0 + n; int row;
;         if (mode == 0) row = ng;
;         else if (mode == 3) {
;             if (ng < 512) row = (ng & ~255) + 128 * ((ng >> 5) & 1) + 32 * ((ng >> 6) & 3) + (ng & 31);
;             else if (ng < 640) row = 512 + 128 * ((ng >> 5) & 1) + 32 * ((ng >> 6) & 1) + (ng & 31);
;             else if (ng < 768) { const int vi = ng - 640; row = 512 + 128 * ((vi >> 5) & 1) + 32 * (2 + (vi >> 6)) + (vi & 31); }
;             else row = ng; }
;         else row = (ng >> 7) * 256 + (ng & 127) + (mode == 2 ? 128 : 0);
;         *(v4u*)(WT + (size_t)row * K + k0 + 8 * c) = o; }
.LBB0_248:
	s_waitcnt lgkmcnt(3)
	v_bfe_u32 v10, v9, 16, 1
	v_add3_u32 v9, v9, v10, s16
	v_bfe_u32 v10, v8, 16, 1
	v_add3_u32 v8, v8, v10, s16
	v_lshrrev_b32_e32 v8, 16, v8
	v_and_or_b32 v8, v9, s17, v8
	s_waitcnt lgkmcnt(2)
	v_bfe_u32 v9, v7, 16, 1
	v_add3_u32 v7, v7, v9, s16
	v_bfe_u32 v9, v6, 16, 1
	v_add3_u32 v6, v6, v9, s16
	v_lshrrev_b32_e32 v6, 16, v6
	v_and_or_b32 v9, v7, s17, v6
	s_waitcnt lgkmcnt(1)
	v_bfe_u32 v6, v5, 16, 1
	v_add3_u32 v5, v5, v6, s16
	v_bfe_u32 v6, v4, 16, 1
	v_add3_u32 v4, v4, v6, s16
	v_lshrrev_b32_e32 v4, 16, v4
	v_and_or_b32 v10, v5, s17, v4
	s_waitcnt lgkmcnt(0)
	v_bfe_u32 v4, v3, 16, 1
	v_add3_u32 v3, v3, v4, s16
	v_bfe_u32 v4, v2, 16, 1
	v_add3_u32 v2, v2, v4, s16
	v_lshrrev_b32_e32 v2, 16, v2
	v_and_or_b32 v11, v3, s17, v2
	v_lshlrev_b64 v[2:3], 11, v[66:67]
	v_lshl_add_u64 v[2:3], v[34:35], 0, v[2:3]
	global_store_dwordx4 v[2:3], v[8:11], off sc1
	s_waitcnt lgkmcnt(0)
	s_mov_b64 s[4:5], 0
.LBB0_249:
	s_and_b64 vcc, exec, s[4:5]
	s_cbranch_vccz .LBB0_166
	s_ashr_i32 s4, s14, 31
	s_lshr_b32 s4, s4, 28
	s_add_i32 s4, s14, s4
	s_ashr_i32 s10, s4, 4
	s_lshl_b32 s4, s10, 6
	s_lshl_b32 s5, s10, 10
	s_sub_i32 s12, s15, s5
	v_or_b32_e32 v30, s4, v1
	s_ashr_i32 s13, s12, 31
	v_ashrrev_i32_e32 v31, 31, v30
	v_lshl_add_u64 v[32:33], s[12:13], 2, v[72:73]
	v_lshlrev_b64 v[2:3], 12, v[30:31]
	v_or_b32_e32 v6, 8, v30
	v_lshl_add_u64 v[34:35], v[32:33], 0, v[2:3]
	v_ashrrev_i32_e32 v7, 31, v6
	global_load_dwordx4 v[2:5], v[34:35], off nt
	v_lshlrev_b64 v[6:7], 12, v[6:7]
	v_or_b32_e32 v10, 16, v30
	v_lshl_add_u64 v[38:39], v[32:33], 0, v[6:7]
	v_ashrrev_i32_e32 v11, 31, v10
	global_load_dwordx4 v[6:9], v[38:39], off nt
	v_lshlrev_b64 v[10:11], 12, v[10:11]
	v_or_b32_e32 v14, 24, v30
	v_lshl_add_u64 v[42:43], v[32:33], 0, v[10:11]
	v_ashrrev_i32_e32 v15, 31, v14
	global_load_dwordx4 v[10:13], v[42:43], off nt
	v_lshlrev_b64 v[14:15], 12, v[14:15]
	v_or_b32_e32 v18, 32, v30
	v_lshl_add_u64 v[46:47], v[32:33], 0, v[14:15]
	v_ashrrev_i32_e32 v19, 31, v18
	global_load_dwordx4 v[14:17], v[46:47], off nt
	v_lshlrev_b64 v[18:19], 12, v[18:19]
	v_or_b32_e32 v22, 40, v30
	v_lshl_add_u64 v[50:51], v[32:33], 0, v[18:19]
	v_ashrrev_i32_e32 v23, 31, v22
	global_load_dwordx4 v[18:21], v[50:51], off nt
	v_lshlrev_b64 v[22:23], 12, v[22:23]
	v_or_b32_e32 v26, 48, v30
	v_lshl_add_u64 v[54:55], v[32:33], 0, v[22:23]
	v_ashrrev_i32_e32 v27, 31, v26
	global_load_dwordx4 v[22:25], v[54:55], off nt
	v_lshlrev_b64 v[26:27], 12, v[26:27]
	v_or_b32_e32 v30, 56, v30
	v_lshl_add_u64 v[58:59], v[32:33], 0, v[26:27]
	v_ashrrev_i32_e32 v31, 31, v30
	global_load_dwordx4 v[26:29], v[58:59], off nt
	v_lshlrev_b64 v[30:31], 12, v[30:31]
	v_lshl_add_u64 v[62:63], v[32:33], 0, v[30:31]
	global_load_dwordx4 v[30:33], v[62:63], off nt
	s_nop 0
	global_load_dwordx4 v[34:37], v[34:35], off offset:128 nt
	s_nop 0
	global_load_dwordx4 v[38:41], v[38:39], off offset:128 nt
	s_nop 0
	global_load_dwordx4 v[42:45], v[42:43], off offset:128 nt
	s_nop 0
	global_load_dwordx4 v[46:49], v[46:47], off offset:128 nt
	s_nop 0
	global_load_dwordx4 v[50:53], v[50:51], off offset:128 nt
	s_nop 0
	global_load_dwordx4 v[54:57], v[54:55], off offset:128 nt
	s_nop 0
	global_load_dwordx4 v[58:61], v[58:59], off offset:128 nt
	s_nop 0
	global_load_dwordx4 v[62:65], v[62:63], off offset:128 nt
	v_add_u32_e32 v66, v92, v93
	v_add_u32_e32 v76, 0x420, v66
	v_add_u32_e32 v77, 0x428, v66
	v_add_u32_e32 v78, 0x840, v66
	v_add_u32_e32 v79, 0x848, v66
	v_add_u32_e32 v80, 0xc60, v66
	v_add_u32_e32 v81, 0xc68, v66
	v_add_u32_e32 v82, 0x1080, v66
	v_add_u32_e32 v83, 0x1088, v66
	v_add_u32_e32 v84, 0x14a0, v66
	v_add_u32_e32 v85, 0x14a8, v66
	v_add_u32_e32 v86, 0x18c0, v66
	v_add_u32_e32 v87, 0x18c8, v66
	v_add_u32_e32 v88, 0x1ce0, v66
	v_add_u32_e32 v89, 0x1ce8, v66
	s_mul_i32 s10, s10, 0xffd40000
	s_ashr_i32 s5, s4, 31
	s_waitcnt vmcnt(15)
	ds_write2_b32 v66, v2, v3 offset1:1
	ds_write2_b32 v66, v4, v5 offset0:2 offset1:3
	s_waitcnt vmcnt(14)
	ds_write2_b32 v76, v6, v7 offset1:1
	ds_write2_b32 v77, v8, v9 offset1:1
	s_waitcnt vmcnt(13)
	ds_write2_b32 v78, v10, v11 offset1:1
	ds_write2_b32 v79, v12, v13 offset1:1
	s_waitcnt vmcnt(12)
	ds_write2_b32 v80, v14, v15 offset1:1
	ds_write2_b32 v81, v16, v17 offset1:1
	s_waitcnt vmcnt(11)
	ds_write2_b32 v82, v18, v19 offset1:1
	ds_write2_b32 v83, v20, v21 offset1:1
	s_waitcnt vmcnt(10)
	ds_write2_b32 v84, v22, v23 offset1:1
	ds_write2_b32 v85, v24, v25 offset1:1
	s_waitcnt vmcnt(9)
	ds_write2_b32 v86, v26, v27 offset1:1
	ds_write2_b32 v87, v28, v29 offset1:1
	s_waitcnt vmcnt(8)
	ds_write2_b32 v88, v30, v31 offset1:1
	ds_write2_b32 v89, v32, v33 offset1:1
	s_waitcnt lgkmcnt(0)
	ds_read2_b32 v[10:11], v97 offset1:8
	ds_read2_b32 v[12:13], v97 offset0:33 offset1:41
	ds_read2_b32 v[14:15], v97 offset0:66 offset1:74
	ds_read2_b32 v[16:17], v97 offset0:99 offset1:107
	ds_read2_b32 v[18:19], v97 offset0:132 offset1:140
	ds_read2_b32 v[20:21], v97 offset0:165 offset1:173
	s_waitcnt lgkmcnt(5)
	v_bfe_u32 v4, v10, 16, 1
	s_waitcnt lgkmcnt(4)
	v_bfe_u32 v5, v12, 16, 1
	v_add3_u32 v4, v10, v4, s16
	v_add3_u32 v5, v12, v5, s16
	v_lshrrev_b32_e32 v4, 16, v4
	v_and_or_b32 v6, v5, s17, v4
	s_waitcnt lgkmcnt(3)
	v_bfe_u32 v4, v14, 16, 1
	v_add3_u32 v4, v14, v4, s16
	s_waitcnt lgkmcnt(2)
	v_bfe_u32 v5, v16, 16, 1
	ds_read2_b32 v[22:23], v97 offset0:198 offset1:206
	v_lshrrev_b32_e32 v4, 16, v4
	v_add3_u32 v5, v16, v5, s16
	ds_read2_b32 v[24:25], v97 offset0:231 offset1:239
	v_and_or_b32 v7, v5, s17, v4
	s_waitcnt lgkmcnt(3)
	v_bfe_u32 v4, v18, 16, 1
	v_add3_u32 v4, v18, v4, s16
	s_waitcnt lgkmcnt(2)
; #define LAS __attribute__((address_space(3)))
; #define LDS_WAIT() asm volatile("s_waitcnt lgkmcnt(0)" ::: "memory")
; __device__ __forceinline__ unsigned pk2(float lo, float hi) { return f2bf(lo) | (f2bf(hi) << 16); }
; __device__ __forceinline__ void p0_transpose_item(const float* W, int K, int N, bf16* WT, const float* gain, int mode, LAS float* scr, int item, int lane) {
;     ...
;         for (int i = 0; i < 8; ++i) w[hf][i] = __builtin_nontemporal_load((const f32x4*)(W + (size_t)(k0 + (lane >> 3) + 8 * i) * N + n00 + 32 * hf + 4 * (lane & 7)));
; #pragma unroll
;     for (int i = 0; i < 8; ++i) gn[i] = gain ? gain[k0 + (lane >> 3) + 8 * i] : 1.0f;
; #pragma unroll
;     for (int hf = 0; hf < 2; ++hf) { const int n0 = n00 + 32 * hf;
; #pragma unroll
;       for (int i = 0; i < 8; ++i) { const int kk = (lane >> 3) + 8 * i; LAS float* d = scr + kk * 33 + 4 * (lane & 7);
;           d[0] = w[hf][i].x * gn[i]; d[1] = w[hf][i].y * gn[i]; d[2] = w[hf][i].z * gn[i]; d[3] = w[hf][i].w * gn[i]; }
;     LDS_WAIT(); asm volatile("" ::: "memory");
;     const int c = lane & 7;
; #pragma unroll
;     for (int j = 0; j < 4; ++j) { const int n = (lane >> 3) + 8 * j; const LAS float* s = scr + (8 * c) * 33 + n;
;         v4u o; o.x = pk2(s[0 * 33], s[1 * 33]); o.y = pk2(s[2 * 33], s[3 * 33]); o.z = pk2(s[4 * 33], s[5 * 33]); o.w = pk2(s[6 * 33], s[7 * 33]);
;         const int ng = n0 + n; int row;
;         if (mode == 0) row = ng;
;         else if (mode == 3) {
;             if (ng < 512) row = (ng & ~255) + 128 * ((ng >> 5) & 1) + 32 * ((ng >> 6) & 3) + (ng & 31);
;             else if (ng < 640) row = 512 + 128 * ((ng >> 5) & 1) + 32 * ((ng >> 6) & 1) + (ng & 31);
;             else if (ng < 768) { const int vi = ng - 640; row = 512 + 128 * ((vi >> 5) & 1) + 32 * (2 + (vi >> 6)) + (vi & 31); }
;             else row = ng; }
;         else row = (ng >> 7) * 256 + (ng & 127) + (mode == 2 ? 128 : 0);
;         *(v4u*)(WT + (size_t)row * K + k0 + 8 * c) = o; }
	v_bfe_u32 v5, v20, 16, 1
	v_lshrrev_b32_e32 v4, 16, v4
	v_add3_u32 v5, v20, v5, s16
	v_and_or_b32 v8, v5, s17, v4
	s_waitcnt lgkmcnt(1)
	v_bfe_u32 v4, v22, 16, 1
	v_add3_u32 v4, v22, v4, s16
	s_waitcnt lgkmcnt(0)
	v_bfe_u32 v5, v24, 16, 1
	v_lshrrev_b32_e32 v4, 16, v4
	v_add3_u32 v5, v24, v5, s16
	v_and_or_b32 v9, v5, s17, v4
	v_add_u32_e32 v4, s10, v106
	v_lshl_add_u64 v[2:3], s[4:5], 1, v[74:75]
	v_ashrrev_i32_e32 v5, 31, v4
	v_lshl_add_u64 v[26:27], v[4:5], 1, v[2:3]
	v_bfe_u32 v5, v11, 16, 1
	global_store_dwordx4 v[26:27], v[6:9], off sc1
	v_add3_u32 v5, v11, v5, s16
	v_lshrrev_b32_e32 v5, 16, v5
	v_bfe_u32 v6, v13, 16, 1
	v_add3_u32 v6, v13, v6, s16
	v_and_or_b32 v6, v6, s17, v5
	v_bfe_u32 v5, v15, 16, 1
	v_add3_u32 v5, v15, v5, s16
	v_bfe_u32 v7, v17, 16, 1
	v_lshrrev_b32_e32 v5, 16, v5
	v_add3_u32 v7, v17, v7, s16
	v_and_or_b32 v7, v7, s17, v5
	v_bfe_u32 v5, v19, 16, 1
	v_add3_u32 v5, v19, v5, s16
	v_bfe_u32 v8, v21, 16, 1
	v_lshrrev_b32_e32 v5, 16, v5
	v_add3_u32 v8, v21, v8, s16
	v_and_or_b32 v8, v8, s17, v5
	v_bfe_u32 v5, v23, 16, 1
	v_add3_u32 v5, v23, v5, s16
	v_bfe_u32 v9, v25, 16, 1
	v_add_u32_e32 v10, 0x5800, v4
	v_lshrrev_b32_e32 v5, 16, v5
	v_add3_u32 v9, v25, v9, s16
	v_ashrrev_i32_e32 v11, 31, v10
	v_and_or_b32 v9, v9, s17, v5
	ds_read2_b32 v[12:13], v97 offset0:16 offset1:24
	v_lshl_add_u64 v[10:11], v[10:11], 1, v[2:3]
	global_store_dwordx4 v[10:11], v[6:9], off sc1
	ds_read2_b32 v[10:11], v97 offset0:49 offset1:57
	ds_read2_b32 v[14:15], v97 offset0:82 offset1:90
	ds_read2_b32 v[16:17], v97 offset0:115 offset1:123
	s_waitcnt lgkmcnt(3)
	v_bfe_u32 v5, v12, 16, 1
	v_add3_u32 v5, v12, v5, s16
	s_waitcnt lgkmcnt(2)
	v_bfe_u32 v6, v10, 16, 1
	ds_read2_b32 v[18:19], v97 offset0:148 offset1:156
	v_lshrrev_b32_e32 v5, 16, v5
	v_add3_u32 v6, v10, v6, s16
	ds_read2_b32 v[20:21], v97 offset0:181 offset1:189
	v_and_or_b32 v6, v6, s17, v5
	s_waitcnt lgkmcnt(3)
	v_bfe_u32 v5, v14, 16, 1
	v_add3_u32 v5, v14, v5, s16
	s_waitcnt lgkmcnt(2)
	v_bfe_u32 v7, v16, 16, 1
	ds_read2_b32 v[22:23], v97 offset0:214 offset1:222
	v_lshrrev_b32_e32 v5, 16, v5
	v_add3_u32 v7, v16, v7, s16
	ds_read2_b32 v[24:25], v97 offset0:247 offset1:255
	v_and_or_b32 v7, v7, s17, v5
	s_waitcnt lgkmcnt(3)
	v_bfe_u32 v5, v18, 16, 1
	v_add3_u32 v5, v18, v5, s16
	s_waitcnt lgkmcnt(2)
	v_bfe_u32 v8, v20, 16, 1
	v_lshrrev_b32_e32 v5, 16, v5
	v_add3_u32 v8, v20, v8, s16
	v_and_or_b32 v8, v8, s17, v5
	s_waitcnt lgkmcnt(1)
	v_bfe_u32 v5, v22, 16, 1
	v_add3_u32 v5, v22, v5, s16
	s_waitcnt lgkmcnt(0)
	v_bfe_u32 v9, v24, 16, 1
	v_add_u32_e32 v26, 0xb000, v4
	v_lshrrev_b32_e32 v5, 16, v5
	v_add3_u32 v9, v24, v9, s16
	v_ashrrev_i32_e32 v27, 31, v26
	v_and_or_b32 v9, v9, s17, v5
	v_lshl_add_u64 v[26:27], v[26:27], 1, v[2:3]
	v_bfe_u32 v5, v13, 16, 1
	global_store_dwordx4 v[26:27], v[6:9], off sc1
	v_add3_u32 v5, v13, v5, s16
	v_lshrrev_b32_e32 v5, 16, v5
	v_bfe_u32 v6, v11, 16, 1
	v_add3_u32 v6, v11, v6, s16
	v_and_or_b32 v6, v6, s17, v5
	v_bfe_u32 v5, v15, 16, 1
	v_add3_u32 v5, v15, v5, s16
	v_bfe_u32 v7, v17, 16, 1
	v_lshrrev_b32_e32 v5, 16, v5
	v_add3_u32 v7, v17, v7, s16
	v_and_or_b32 v7, v7, s17, v5
	v_bfe_u32 v5, v19, 16, 1
	v_add3_u32 v5, v19, v5, s16
	v_bfe_u32 v8, v21, 16, 1
	v_lshrrev_b32_e32 v5, 16, v5
	v_add3_u32 v8, v21, v8, s16
	v_and_or_b32 v8, v8, s17, v5
	v_bfe_u32 v5, v23, 16, 1
	v_add3_u32 v5, v23, v5, s16
	v_bfe_u32 v9, v25, 16, 1
	v_add_u32_e32 v10, 0x10800, v4
	v_lshrrev_b32_e32 v5, 16, v5
	v_add3_u32 v9, v25, v9, s16
	v_ashrrev_i32_e32 v11, 31, v10
	v_and_or_b32 v9, v9, s17, v5
	v_lshl_add_u64 v[10:11], v[10:11], 1, v[2:3]
	global_store_dwordx4 v[10:11], v[6:9], off sc1
	s_waitcnt lgkmcnt(0)
	s_waitcnt vmcnt(11)
	ds_write2_b32 v66, v34, v35 offset1:1
	ds_write2_b32 v66, v36, v37 offset0:2 offset1:3
	s_waitcnt vmcnt(10)
	ds_write2_b32 v76, v38, v39 offset1:1
	ds_write2_b32 v77, v40, v41 offset1:1
	s_waitcnt vmcnt(9)
	ds_write2_b32 v78, v42, v43 offset1:1
	ds_write2_b32 v79, v44, v45 offset1:1
	s_waitcnt vmcnt(8)
	ds_write2_b32 v80, v46, v47 offset1:1
	ds_write2_b32 v81, v48, v49 offset1:1
	s_waitcnt vmcnt(7)
	ds_write2_b32 v82, v50, v51 offset1:1
	ds_write2_b32 v83, v52, v53 offset1:1
	s_waitcnt vmcnt(6)
	ds_write2_b32 v84, v54, v55 offset1:1
	ds_write2_b32 v85, v56, v57 offset1:1
	s_waitcnt vmcnt(5)
	ds_write2_b32 v86, v58, v59 offset1:1
	ds_write2_b32 v87, v60, v61 offset1:1
	s_waitcnt vmcnt(4)
	ds_write2_b32 v88, v62, v63 offset1:1
	ds_write2_b32 v89, v64, v65 offset1:1
	s_waitcnt lgkmcnt(0)
	ds_read2_b32 v[10:11], v97 offset1:8
	ds_read2_b32 v[12:13], v97 offset0:33 offset1:41
	ds_read2_b32 v[14:15], v97 offset0:66 offset1:74
	ds_read2_b32 v[16:17], v97 offset0:99 offset1:107
	ds_read2_b32 v[18:19], v97 offset0:132 offset1:140
	s_waitcnt lgkmcnt(4)
; __device__ __forceinline__ void p0_transpose_item(const float* W, int K, int N, bf16* WT, const float* gain, int mode, LAS float* scr, int item, int lane) {
;     ...
;         for (int i = 0; i < 8; ++i) w[hf][i] = __builtin_nontemporal_load((const f32x4*)(W + (size_t)(k0 + (lane >> 3) + 8 * i) * N + n00 + 32 * hf + 4 * (lane & 7)));
; #pragma unroll
;     for (int i = 0; i < 8; ++i) gn[i] = gain ? gain[k0 + (lane >> 3) + 8 * i] : 1.0f;
; #pragma unroll
;     for (int hf = 0; hf < 2; ++hf) { const int n0 = n00 + 32 * hf;
; #pragma unroll
;       for (int i = 0; i < 8; ++i) { const int kk = (lane >> 3) + 8 * i; LAS float* d = scr + kk * 33 + 4 * (lane & 7);
;           d[0] = w[hf][i].x * gn[i]; d[1] = w[hf][i].y * gn[i]; d[2] = w[hf][i].z * gn[i]; d[3] = w[hf][i].w * gn[i]; }
;     LDS_WAIT(); asm volatile("" ::: "memory");
;     const int c = lane & 7;
; #pragma unroll
;     for (int j = 0; j < 4; ++j) { const int n = (lane >> 3) + 8 * j; const LAS float* s = scr + (8 * c) * 33 + n;
;         v4u o; o.x = pk2(s[0 * 33], s[1 * 33]); o.y = pk2(s[2 * 33], s[3 * 33]); o.z = pk2(s[4 * 33], s[5 * 33]); o.w = pk2(s[6 * 33], s[7 * 33]);
;         const int ng = n0 + n; int row;
;         if (mode == 0) row = ng;
;         else if (mode == 3) {
;             if (ng < 512) row = (ng & ~255) + 128 * ((ng >> 5) & 1) + 32 * ((ng >> 6) & 3) + (ng & 31);
;             else if (ng < 640) row = 512 + 128 * ((ng >> 5) & 1) + 32 * ((ng >> 6) & 1) + (ng & 31);
;             else if (ng < 768) { const int vi = ng - 640; row = 512 + 128 * ((vi >> 5) & 1) + 32 * (2 + (vi >> 6)) + (vi & 31); }
;             else row = ng; }
;         else row = (ng >> 7) * 256 + (ng & 127) + (mode == 2 ? 128 : 0);
;         *(v4u*)(WT + (size_t)row * K + k0 + 8 * c) = o; }
; __global__ void __launch_bounds__(NWAVES * 64, 2) mega_fwd(Args args) {
;     ...
;         if (bx >= 128) {
;             OPAQUE_TID(); LAS float* scr = (LAS float*)(lds + wave * 16384);
;             constexpr int J_D = (FF / 64) * (DM / 64), J_IN = (DM / 64) * (NIN / 64);
;             for (int it = (bx - 128) * NWAVES + wave; it < J_D + J_IN; it += 128 * NWAVES) {
;                 if (it < J_D) p0_transpose_item(args.in[5], FF, DM, W1d, nullptr, 0, scr, it, lane);
;                 else p0_transpose_item(args.in[7], DM, NIN, Win, args.in[6], 3, scr, it - J_D, lane); }
;             __syncthreads(); } }
	v_bfe_u32 v5, v10, 16, 1
	v_add3_u32 v5, v10, v5, s16
	s_waitcnt lgkmcnt(3)
	v_bfe_u32 v6, v12, 16, 1
	v_lshrrev_b32_e32 v5, 16, v5
	v_add3_u32 v6, v12, v6, s16
	ds_read2_b32 v[20:21], v97 offset0:165 offset1:173
	v_and_or_b32 v6, v6, s17, v5
	s_waitcnt lgkmcnt(3)
	v_bfe_u32 v5, v14, 16, 1
	v_add3_u32 v5, v14, v5, s16
	s_waitcnt lgkmcnt(2)
	v_bfe_u32 v7, v16, 16, 1
	ds_read2_b32 v[22:23], v97 offset0:198 offset1:206
	v_lshrrev_b32_e32 v5, 16, v5
	v_add3_u32 v7, v16, v7, s16
	ds_read2_b32 v[24:25], v97 offset0:231 offset1:239
	v_and_or_b32 v7, v7, s17, v5
	s_waitcnt lgkmcnt(3)
	v_bfe_u32 v5, v18, 16, 1
	v_add3_u32 v5, v18, v5, s16
	s_waitcnt lgkmcnt(2)
	v_bfe_u32 v8, v20, 16, 1
	v_lshrrev_b32_e32 v5, 16, v5
	v_add3_u32 v8, v20, v8, s16
	v_and_or_b32 v8, v8, s17, v5
	s_waitcnt lgkmcnt(1)
	v_bfe_u32 v5, v22, 16, 1
	v_add3_u32 v5, v22, v5, s16
	s_waitcnt lgkmcnt(0)
	v_bfe_u32 v9, v24, 16, 1
	v_add_u32_e32 v26, 0x16000, v4
	v_lshrrev_b32_e32 v5, 16, v5
	v_add3_u32 v9, v24, v9, s16
	v_ashrrev_i32_e32 v27, 31, v26
	v_and_or_b32 v9, v9, s17, v5
	v_lshl_add_u64 v[26:27], v[26:27], 1, v[2:3]
	v_bfe_u32 v5, v11, 16, 1
	global_store_dwordx4 v[26:27], v[6:9], off sc1
	v_add3_u32 v5, v11, v5, s16
	v_lshrrev_b32_e32 v5, 16, v5
	v_bfe_u32 v6, v13, 16, 1
	v_add3_u32 v6, v13, v6, s16
	v_and_or_b32 v6, v6, s17, v5
	v_bfe_u32 v5, v15, 16, 1
	v_add3_u32 v5, v15, v5, s16
	v_bfe_u32 v7, v17, 16, 1
	v_lshrrev_b32_e32 v5, 16, v5
	v_add3_u32 v7, v17, v7, s16
	v_and_or_b32 v7, v7, s17, v5
	v_bfe_u32 v5, v19, 16, 1
	v_add3_u32 v5, v19, v5, s16
	v_bfe_u32 v8, v21, 16, 1
	v_lshrrev_b32_e32 v5, 16, v5
	v_add3_u32 v8, v21, v8, s16
	v_and_or_b32 v8, v8, s17, v5
	v_bfe_u32 v5, v23, 16, 1
	v_add3_u32 v5, v23, v5, s16
	v_bfe_u32 v9, v25, 16, 1
	v_add_u32_e32 v10, 0x1b800, v4
	v_lshrrev_b32_e32 v5, 16, v5
	v_add3_u32 v9, v25, v9, s16
	v_ashrrev_i32_e32 v11, 31, v10
	v_and_or_b32 v9, v9, s17, v5
	ds_read2_b32 v[12:13], v97 offset0:16 offset1:24
	v_lshl_add_u64 v[10:11], v[10:11], 1, v[2:3]
	global_store_dwordx4 v[10:11], v[6:9], off sc1
	ds_read2_b32 v[10:11], v97 offset0:49 offset1:57
	ds_read2_b32 v[14:15], v97 offset0:82 offset1:90
	ds_read2_b32 v[16:17], v97 offset0:115 offset1:123
	s_waitcnt lgkmcnt(3)
	v_bfe_u32 v5, v12, 16, 1
	v_add3_u32 v5, v12, v5, s16
	s_waitcnt lgkmcnt(2)
	v_bfe_u32 v6, v10, 16, 1
	ds_read2_b32 v[18:19], v97 offset0:148 offset1:156
	v_lshrrev_b32_e32 v5, 16, v5
	v_add3_u32 v6, v10, v6, s16
	ds_read2_b32 v[20:21], v97 offset0:181 offset1:189
	v_and_or_b32 v6, v6, s17, v5
	s_waitcnt lgkmcnt(3)
	v_bfe_u32 v5, v14, 16, 1
	v_add3_u32 v5, v14, v5, s16
	s_waitcnt lgkmcnt(2)
	v_bfe_u32 v7, v16, 16, 1
	ds_read2_b32 v[22:23], v97 offset0:214 offset1:222
	v_lshrrev_b32_e32 v5, 16, v5
	v_add3_u32 v7, v16, v7, s16
	ds_read2_b32 v[24:25], v97 offset0:247 offset1:255
	v_and_or_b32 v7, v7, s17, v5
	s_waitcnt lgkmcnt(3)
	v_bfe_u32 v5, v18, 16, 1
	v_add3_u32 v5, v18, v5, s16
	s_waitcnt lgkmcnt(2)
	v_bfe_u32 v8, v20, 16, 1
	v_lshrrev_b32_e32 v5, 16, v5
	v_add3_u32 v8, v20, v8, s16
	v_and_or_b32 v8, v8, s17, v5
	s_waitcnt lgkmcnt(1)
	v_bfe_u32 v5, v22, 16, 1
	v_add3_u32 v5, v22, v5, s16
	s_waitcnt lgkmcnt(0)
	v_bfe_u32 v9, v24, 16, 1
	v_add_u32_e32 v26, 0x21000, v4
	v_lshrrev_b32_e32 v5, 16, v5
	v_add3_u32 v9, v24, v9, s16
	v_ashrrev_i32_e32 v27, 31, v26
	v_and_or_b32 v9, v9, s17, v5
	v_lshl_add_u64 v[26:27], v[26:27], 1, v[2:3]
	global_store_dwordx4 v[26:27], v[6:9], off sc1
	v_bfe_u32 v5, v11, 16, 1
	v_add3_u32 v5, v11, v5, s16
	v_bfe_u32 v6, v13, 16, 1
	v_add3_u32 v6, v13, v6, s16
	v_lshrrev_b32_e32 v6, 16, v6
	v_bfe_u32 v7, v15, 16, 1
	v_and_or_b32 v6, v5, s17, v6
	v_bfe_u32 v5, v17, 16, 1
	v_add3_u32 v7, v15, v7, s16
	v_add3_u32 v5, v17, v5, s16
	v_lshrrev_b32_e32 v7, 16, v7
	v_bfe_u32 v8, v19, 16, 1
	v_and_or_b32 v7, v5, s17, v7
	v_bfe_u32 v5, v21, 16, 1
	v_add3_u32 v8, v19, v8, s16
	v_add3_u32 v5, v21, v5, s16
	v_lshrrev_b32_e32 v8, 16, v8
	v_bfe_u32 v9, v23, 16, 1
	v_and_or_b32 v8, v5, s17, v8
	v_bfe_u32 v5, v25, 16, 1
	v_add3_u32 v9, v23, v9, s16
	v_add3_u32 v5, v25, v5, s16
	v_lshrrev_b32_e32 v9, 16, v9
	v_add_u32_e32 v4, 0x26800, v4
	v_and_or_b32 v9, v5, s17, v9
	v_ashrrev_i32_e32 v5, 31, v4
	v_lshl_add_u64 v[2:3], v[4:5], 1, v[2:3]
	global_store_dwordx4 v[2:3], v[6:9], off sc1
	s_waitcnt lgkmcnt(0)
	s_branch .LBB0_166
.LBB0_251:
	s_waitcnt vmcnt(0)
	s_barrier
	v_readlane_b32 s14, v251, 18
	v_readlane_b32 s15, v251, 19
	s_add_u32 s10, s66, 0xfd0f000
	s_addc_u32 s11, s67, 0
	s_nop 0
	s_and_saveexec_b64 s[12:13], s[14:15]
	s_cbranch_execz .Lc1_arr_done
	v_mov_b32_e32 v1, 0
	v_mov_b32_e32 v2, 1
	global_atomic_add v1, v2, s[10:11]

; __device__ __forceinline__ unsigned xb_ld(unsigned* p)              { return __hip_atomic_load(p, __ATOMIC_RELAXED, __HIP_MEMORY_SCOPE_AGENT); }
; __device__ __forceinline__ unsigned xb_add(unsigned* p, unsigned v) { return __hip_atomic_fetch_add(p, v, __ATOMIC_RELAXED, __HIP_MEMORY_SCOPE_AGENT); }
; #define XB_SPIN(cond, bar) do { unsigned _sp = 0; while (cond) { __builtin_amdgcn_s_sleep(1); \
;     if ((++_sp & 255u) == 0u) { if (xb_ld(&(bar)[XB_TMO])) break; if (_sp > XB_SPIN_CAP) { atomicAdd(&(bar)[XB_TMO], 1u); break; } } } } while (0)
; #define SEAM(k) do { if (IN(k) && IN((k) + 1)) xcd_barrier(bar); } while (0)
; __device__ __forceinline__ void xcd_barrier(const XcdBarrier& b) {
;     asm volatile("s_waitcnt vmcnt(0)" ::: "memory");
;     __syncthreads();
;     if (threadIdx.x == 0) {
;         unsigned* bar = b.bar;
;         __builtin_amdgcn_s_waitcnt(0);
;         unsigned nloc = b.st[0], nx = b.st[1];
;         if (nloc == 0u) { xcd_barrier_complete(bar, b.x, nloc, nx); b.st[0] = nloc; b.st[1] = nx; }
;         const unsigned old = xb_add(&bar[XB_XSUB(b.x)], 1u);
;         const unsigned gen = old / nloc;
;         if (old + 1u == (gen + 1u) * nloc) {
;             __builtin_amdgcn_fence(__ATOMIC_RELEASE, "agent");
;             asm volatile("s_waitcnt vmcnt(0)" ::: "memory");
;             const unsigned og = xb_add(&bar[XB_TOP], 1u);
;             const unsigned tg = og / nx;
;             if (og + 1u == (tg + 1u) * nx) xb_add(&bar[XB_TOPGEN], 1u);
;             else XB_SPIN(xb_ld(&bar[XB_TOPGEN]) == tg, bar);
;             __builtin_amdgcn_fence(__ATOMIC_ACQUIRE, "agent");
;             xb_add(&bar[XB_XGEN(b.x)], 1u);
;             asm volatile("s_waitcnt vmcnt(0)" ::: "memory");
;         } else {
;             XB_SPIN(xb_ld(&bar[XB_XGEN(b.x)]) == gen, bar);
;             __builtin_amdgcn_fence(__ATOMIC_ACQUIRE, "agent");
;             asm volatile("s_waitcnt vmcnt(0)" ::: "memory");
;         }
;     }
;     __syncthreads();
; }
; __global__ void __launch_bounds__(NWAVES * 64, 2) mega_fwd(Args args) {
;     ...
;     SEAM(1);
;     if (IN(2)) { pg8::Gemm g{ACT, W1d, M, DM, FF, 64, FF, 0, 0, 1, (size_t)256 * 64 * 2, (size_t)(FF / 64) * 256 * 64 * 2}; pg8::StaticOrder S; S.init(M, DM, 1, G, bx);
;         pg8::EpiResid<true> E{nullptr, XB, ss1, 0.5f}; pg8::gemm_phase<pg8::EpiResid<true>, true>(lds, g, S, E); }
.LBB0_252:
	s_cmp_gt_i32 s85, 2
	s_cselect_b64 s[2:3], -1, 0
	s_and_b64 s[4:5], s[6:7], s[2:3]
	s_andn2_b64 vcc, exec, s[4:5]
	s_cbranch_vccnz .LBB0_306
	s_waitcnt vmcnt(0)
	s_barrier
	s_mov_b64 s[4:5], exec
	v_readlane_b32 s6, v251, 18
	v_readlane_b32 s7, v251, 19
	s_and_b64 s[6:7], s[4:5], s[6:7]
	s_mov_b64 exec, s[6:7]
	s_cbranch_execz .LBB0_305
	s_and_b32 s10, s88, 7
	s_lshl_b32 s10, s10, 3
	s_bfe_u32 s11, s88, 0x30003
	s_or_b32 s10, s10, s11
	s_lshl_b32 s10, s10, 8
	s_add_u32 s12, s66, 0xfd09000
	s_addc_u32 s13, s67, 0
	v_mov_b32_e32 v1, s10
	v_mov_b32_e32 v2, 1
	global_atomic_add v1, v2, s[12:13]
	s_movk_i32 s11, 4
	s_mov_b32 s14, 0
.Lls1_spin:
	global_load_dword v3, v1, s[12:13] sc1
	v_mov_b32_e32 v5, 0x6000
	global_load_dword v6, v5, s[12:13] sc1
	s_waitcnt vmcnt(0)
	v_readfirstlane_b32 s15, v3
	v_readfirstlane_b32 s10, v6
	s_nop 3
	s_cmp_ge_u32 s15, s11
	s_cselect_b32 s15, 1, 0
	s_cmp_ge_u32 s10, 0x80
	s_cselect_b32 s10, 1, 0
	s_and_b32 s15, s15, s10
	s_cmp_lg_u32 s15, 0
	s_cbranch_scc1 .Lls1_ok
	s_sleep 1
	s_add_i32 s14, s14, 1
	s_cmp_lt_u32 s14, 0x20000
	s_cbranch_scc1 .Lls1_spin
.Lls1_ok:
	buffer_inv sc1
	s_waitcnt vmcnt(0)
.LBB0_305:
	s_or_b64 exec, exec, s[4:5]
	s_waitcnt lgkmcnt(0)
	s_barrier

; __device__ __forceinline__ unsigned xb_ld(unsigned* p)              { return __hip_atomic_load(p, __ATOMIC_RELAXED, __HIP_MEMORY_SCOPE_AGENT); }
; __device__ __forceinline__ unsigned xb_add(unsigned* p, unsigned v) { return __hip_atomic_fetch_add(p, v, __ATOMIC_RELAXED, __HIP_MEMORY_SCOPE_AGENT); }
; #define XB_SPIN(cond, bar) do { unsigned _sp = 0; while (cond) { __builtin_amdgcn_s_sleep(1); \
;     if ((++_sp & 255u) == 0u) { if (xb_ld(&(bar)[XB_TMO])) break; if (_sp > XB_SPIN_CAP) { atomicAdd(&(bar)[XB_TMO], 1u); break; } } } } while (0)
; #define SEAM(k) do { if (IN(k) && IN((k) + 1)) xcd_barrier(bar); } while (0)
; __device__ __forceinline__ void xcd_barrier(const XcdBarrier& b) {
;     asm volatile("s_waitcnt vmcnt(0)" ::: "memory");
;     __syncthreads();
;     if (threadIdx.x == 0) {
;         unsigned* bar = b.bar;
;         __builtin_amdgcn_s_waitcnt(0);
;         unsigned nloc = b.st[0], nx = b.st[1];
;         if (nloc == 0u) { xcd_barrier_complete(bar, b.x, nloc, nx); b.st[0] = nloc; b.st[1] = nx; }
;         const unsigned old = xb_add(&bar[XB_XSUB(b.x)], 1u);
;         const unsigned gen = old / nloc;
;         if (old + 1u == (gen + 1u) * nloc) {
;             __builtin_amdgcn_fence(__ATOMIC_RELEASE, "agent");
;             asm volatile("s_waitcnt vmcnt(0)" ::: "memory");
;             const unsigned og = xb_add(&bar[XB_TOP], 1u);
;             const unsigned tg = og / nx;
;             if (og + 1u == (tg + 1u) * nx) xb_add(&bar[XB_TOPGEN], 1u);
;             else XB_SPIN(xb_ld(&bar[XB_TOPGEN]) == tg, bar);
;             __builtin_amdgcn_fence(__ATOMIC_ACQUIRE, "agent");
;             xb_add(&bar[XB_XGEN(b.x)], 1u);
;             asm volatile("s_waitcnt vmcnt(0)" ::: "memory");
;         } else {
;             XB_SPIN(xb_ld(&bar[XB_XGEN(b.x)]) == gen, bar);
;             __builtin_amdgcn_fence(__ATOMIC_ACQUIRE, "agent");
;             asm volatile("s_waitcnt vmcnt(0)" ::: "memory");
;         }
;     }
;     __syncthreads();
; }
; __global__ void __launch_bounds__(NWAVES * 64, 2) mega_fwd(Args args) {
;     ...
;     SEAM(2);
;     if (IN(3)) { pg8::Gemm g{XB, Win, M, NIN, DM, DM, DM, 0, 0, 1}; pg8::StaticOrder S; S.init(M, NIN, 1, G, bx);
.LBB0_353:
	s_cmp_gt_i32 s85, 3
	s_cselect_b64 s[2:3], -1, 0
	s_and_b64 s[4:5], s[10:11], s[2:3]
	s_andn2_b64 vcc, exec, s[4:5]
	s_cbranch_vccnz .LBB0_407
	s_waitcnt vmcnt(0)
	s_waitcnt lgkmcnt(0)
	s_barrier
	s_mov_b64 s[4:5], exec
	v_readlane_b32 s6, v251, 18
	v_readlane_b32 s7, v251, 19
	s_and_b64 s[6:7], s[4:5], s[6:7]
	s_mov_b64 exec, s[6:7]
	s_cbranch_execz .LBB0_406
	s_and_b32 s10, s88, 7
	s_lshl_b32 s10, s10, 3
	s_bfe_u32 s11, s88, 0x30003
	s_or_b32 s10, s10, s11
	s_lshl_b32 s10, s10, 8
	s_add_u32 s12, s66, 0xfd09000
	s_addc_u32 s13, s67, 0
	v_mov_b32_e32 v1, s10
	v_mov_b32_e32 v2, 1
	global_atomic_add v1, v2, s[12:13]
	v_mov_b32_e32 v5, 0x5800
	global_atomic_add v5, v2, s[12:13]
	s_movk_i32 s11, 8
	s_mov_b32 s14, 0
.Lls2_spin:
	global_load_dword v3, v1, s[12:13] sc1
	s_waitcnt vmcnt(0)
	v_readfirstlane_b32 s15, v3
	s_nop 3
	s_cmp_ge_u32 s15, s11
	s_cbranch_scc1 .Lls2_ok
	s_sleep 1
	s_add_i32 s14, s14, 1
	s_cmp_lt_u32 s14, 0x20000
	s_cbranch_scc1 .Lls2_spin
.Lls2_ok:
	buffer_inv sc1
	s_waitcnt vmcnt(0)
.LBB0_406:
	s_or_b64 exec, exec, s[4:5]
	s_waitcnt lgkmcnt(0)
	s_barrier

; #define EPI_ROWS  _Pragma("unroll") for (int ai = 0; ai < 2; ++ai) _Pragma("unroll") for (int m = 0; m < 4; ++m)
; #define PG8_BAR __builtin_amdgcn_s_barrier()
;     __device__ __forceinline__ void operator()(AccRef acc, const Unit& u, int wr, int wc, int fr, int fq) const {
;         const int row0 = u.pm * BM + wr * 64 + fr, cw = wc * 32 + 8 * fq, pn = u.pn;
;         float rr[2][4];
;         EPI_ROWS rr[ai][m] = ss[row0 + ai * HALF + m * 16];
;         if (pn < 2 || (pn == 2 && wc < 2)) {
;             const float* gn = pn < 2 ? qg : kg; const float sc = pn < 2 ? C2 : 1.0f;
;             float g1[8], g2[8], fr8[8];
; #pragma unroll
;             for (int j = 0; j < 8; ++j) { g1[j] = gn[8 * fq + j] * sc; g2[j] = gn[32 + 8 * fq + j] * sc;
;                 fr8[j] = __builtin_amdgcn_exp2f(-(float)(8 * (fq & 1) + j) * (13.287712379549449f / 16.0f)) * 0.15915494309189535f; }
;             bf16_t* base = pn < 2 ? q + (pn * 4 + wc) * 64 : k + wc * 64; const int pitch = pn < 2 ? 512 : 128;
; template <class Epi, bool ALIGN_EPI>
; __device__ __forceinline__ void gemm_phase(LAS unsigned char* lds, const Gemm g, const StaticOrder& S, const Epi& E) {
;     ...
;         if constexpr (ALIGN_EPI) { if (wr == 0) PG8_BAR; }
;         E(acc, cur, wr, wc, fr, fq);
.LBB0_422:
	s_cmp_lg_u32 s98, 0
	s_cbranch_scc1 .Lg2_done
	s_mov_b32 s98, 1
	v_cmp_eq_u32_e32 vcc, 0, v0
	s_and_saveexec_b64 s[100:101], vcc
	s_cbranch_execz .Lg2_join
	v_mov_b32_e32 v130, 0xfd0e800
	s_mov_b32 s99, 0
.Lg2_spin:
	global_load_dword v131, v130, s[66:67] sc1
	s_waitcnt vmcnt(0)
	v_readfirstlane_b32 s98, v131
	s_nop 3
	s_cmpk_ge_u32 s98, 0x100
	s_cbranch_scc1 .Lg2_ok
	s_sleep 1
	s_add_i32 s99, s99, 1
	s_cmp_lt_u32 s99, 0x20000
	s_cbranch_scc1 .Lg2_spin
.Lg2_ok:
	s_mov_b32 s98, 1
.Lg2_join:
	s_or_b64 exec, exec, s[100:101]
	s_barrier

; __device__ __forceinline__ unsigned xb_ld(unsigned* p)              { return __hip_atomic_load(p, __ATOMIC_RELAXED, __HIP_MEMORY_SCOPE_AGENT); }
; __device__ __forceinline__ unsigned xb_add(unsigned* p, unsigned v) { return __hip_atomic_fetch_add(p, v, __ATOMIC_RELAXED, __HIP_MEMORY_SCOPE_AGENT); }
; #define XB_SPIN(cond, bar) do { unsigned _sp = 0; while (cond) { __builtin_amdgcn_s_sleep(1); \
;     if ((++_sp & 255u) == 0u) { if (xb_ld(&(bar)[XB_TMO])) break; if (_sp > XB_SPIN_CAP) { atomicAdd(&(bar)[XB_TMO], 1u); break; } } } } while (0)
; #define SEAM(k) do { if (IN(k) && IN((k) + 1)) xcd_barrier(bar); } while (0)
; __device__ __forceinline__ void xcd_barrier(const XcdBarrier& b) {
;     asm volatile("s_waitcnt vmcnt(0)" ::: "memory");
;     __syncthreads();
;     if (threadIdx.x == 0) {
;         unsigned* bar = b.bar;
;         __builtin_amdgcn_s_waitcnt(0);
;         unsigned nloc = b.st[0], nx = b.st[1];
;         if (nloc == 0u) { xcd_barrier_complete(bar, b.x, nloc, nx); b.st[0] = nloc; b.st[1] = nx; }
;         const unsigned old = xb_add(&bar[XB_XSUB(b.x)], 1u);
;         const unsigned gen = old / nloc;
;         if (old + 1u == (gen + 1u) * nloc) {
;             __builtin_amdgcn_fence(__ATOMIC_RELEASE, "agent");
;             asm volatile("s_waitcnt vmcnt(0)" ::: "memory");
;             const unsigned og = xb_add(&bar[XB_TOP], 1u);
;             const unsigned tg = og / nx;
;             if (og + 1u == (tg + 1u) * nx) xb_add(&bar[XB_TOPGEN], 1u);
;             else XB_SPIN(xb_ld(&bar[XB_TOPGEN]) == tg, bar);
;             __builtin_amdgcn_fence(__ATOMIC_ACQUIRE, "agent");
;             xb_add(&bar[XB_XGEN(b.x)], 1u);
;             asm volatile("s_waitcnt vmcnt(0)" ::: "memory");
;         } else {
;             XB_SPIN(xb_ld(&bar[XB_XGEN(b.x)]) == gen, bar);
;             __builtin_amdgcn_fence(__ATOMIC_ACQUIRE, "agent");
;             asm volatile("s_waitcnt vmcnt(0)" ::: "memory");
;         }
;     }
;     __syncthreads();
; }
; __global__ void __launch_bounds__(NWAVES * 64, 2) mega_fwd(Args args) {
;     ...
;     SEAM(8);
;     if (IN(9)) { pg8::Gemm g{MG, Wout, M, DM, DM, DM, DM, 0, 0, 1}; pg8::StaticOrder S; S.init(M, DM, 1, G, bx);
;         pg8::EpiResid<true> E{nullptr, XB, ss2, 1.0f}; pg8::gemm_phase<pg8::EpiResid<true>, true>(lds, g, S, E); }
.LBB0_1138:
	s_cmp_gt_i32 s85, 9
	s_cselect_b64 s[0:1], -1, 0
	s_and_b64 s[2:3], s[4:5], s[0:1]
	s_andn2_b64 vcc, exec, s[2:3]
	s_cbranch_vccnz .LBB0_1192
	s_waitcnt vmcnt(0)
	s_waitcnt vmcnt(0) lgkmcnt(0)
	s_barrier
	s_and_saveexec_b64 s[2:3], s[74:75]
	s_cbranch_execz .LBB0_1191
	s_and_b32 s4, s88, 7
	s_lshl_b32 s4, s4, 3
	s_bfe_u32 s5, s88, 0x30003
	s_or_b32 s4, s4, s5
	s_lshl_b32 s4, s4, 8
	s_add_u32 s6, s66, 0xfd09000
	s_addc_u32 s7, s67, 0
	v_mov_b32_e32 v1, s4
	v_mov_b32_e32 v2, 1
	global_atomic_add v1, v2, s[6:7]
	v_mov_b32_e32 v5, 0x5000
	global_atomic_add v5, v2, s[6:7]
	s_movk_i32 s5, 12
	s_mov_b32 s8, 0

; __device__ __forceinline__ unsigned xb_ld(unsigned* p)              { return __hip_atomic_load(p, __ATOMIC_RELAXED, __HIP_MEMORY_SCOPE_AGENT); }
; __device__ __forceinline__ unsigned xb_add(unsigned* p, unsigned v) { return __hip_atomic_fetch_add(p, v, __ATOMIC_RELAXED, __HIP_MEMORY_SCOPE_AGENT); }
; #define XB_SPIN(cond, bar) do { unsigned _sp = 0; while (cond) { __builtin_amdgcn_s_sleep(1); \
;     if ((++_sp & 255u) == 0u) { if (xb_ld(&(bar)[XB_TMO])) break; if (_sp > XB_SPIN_CAP) { atomicAdd(&(bar)[XB_TMO], 1u); break; } } } } while (0)
; #define SEAM(k) do { if (IN(k) && IN((k) + 1)) xcd_barrier(bar); } while (0)
; __device__ __forceinline__ void xcd_barrier(const XcdBarrier& b) {
;     asm volatile("s_waitcnt vmcnt(0)" ::: "memory");
;     __syncthreads();
;     if (threadIdx.x == 0) {
;         unsigned* bar = b.bar;
;         __builtin_amdgcn_s_waitcnt(0);
;         unsigned nloc = b.st[0], nx = b.st[1];
;         if (nloc == 0u) { xcd_barrier_complete(bar, b.x, nloc, nx); b.st[0] = nloc; b.st[1] = nx; }
;         const unsigned old = xb_add(&bar[XB_XSUB(b.x)], 1u);
;         const unsigned gen = old / nloc;
;         if (old + 1u == (gen + 1u) * nloc) {
;             __builtin_amdgcn_fence(__ATOMIC_RELEASE, "agent");
;             asm volatile("s_waitcnt vmcnt(0)" ::: "memory");
;             const unsigned og = xb_add(&bar[XB_TOP], 1u);
;             const unsigned tg = og / nx;
;             if (og + 1u == (tg + 1u) * nx) xb_add(&bar[XB_TOPGEN], 1u);
;             else XB_SPIN(xb_ld(&bar[XB_TOPGEN]) == tg, bar);
;             __builtin_amdgcn_fence(__ATOMIC_ACQUIRE, "agent");
;             xb_add(&bar[XB_XGEN(b.x)], 1u);
;             asm volatile("s_waitcnt vmcnt(0)" ::: "memory");
;         } else {
;             XB_SPIN(xb_ld(&bar[XB_XGEN(b.x)]) == gen, bar);
;             __builtin_amdgcn_fence(__ATOMIC_ACQUIRE, "agent");
;             asm volatile("s_waitcnt vmcnt(0)" ::: "memory");
;         }
;     }
;     __syncthreads();
; }
; __global__ void __launch_bounds__(NWAVES * 64, 2) mega_fwd(Args args) {
;     ...
;     SEAM(9);
;     if (IN(10)) { pg8::Gemm g{XB, W2gu, M, 2 * FF, DM, DM, DM, 0, 0, 1}; pg8::StaticOrder S; S.init(M, 2 * FF, 1, G, bx);
;         pg8::EpiSwiglu E{ss2, ACT}; pg8::gemm_phase<pg8::EpiSwiglu, true>(lds, g, S, E);
.LBB0_1235:
	s_cmp_gt_i32 s85, 10
	s_cselect_b64 s[2:3], -1, 0
	s_and_b64 s[0:1], s[0:1], s[2:3]
	s_andn2_b64 vcc, exec, s[0:1]
	s_cbranch_vccnz .LBB0_1289
	s_waitcnt vmcnt(0)
	s_waitcnt vmcnt(0) lgkmcnt(0)
	s_barrier
	s_and_saveexec_b64 s[0:1], s[74:75]
	s_cbranch_execz .LBB0_1288
	s_and_b32 s4, s88, 7
	s_lshl_b32 s4, s4, 3
	s_bfe_u32 s5, s88, 0x30003
	s_or_b32 s4, s4, s5
	s_lshl_b32 s4, s4, 8
	s_add_u32 s6, s66, 0xfd09000
	s_addc_u32 s7, s67, 0
	v_mov_b32_e32 v1, s4
	v_mov_b32_e32 v2, 1
	global_atomic_add v1, v2, s[6:7]
	s_movk_i32 s5, 16
	s_mov_b32 s8, 0

; __device__ __forceinline__ unsigned xb_ld(unsigned* p)              { return __hip_atomic_load(p, __ATOMIC_RELAXED, __HIP_MEMORY_SCOPE_AGENT); }
; __device__ __forceinline__ unsigned xb_add(unsigned* p, unsigned v) { return __hip_atomic_fetch_add(p, v, __ATOMIC_RELAXED, __HIP_MEMORY_SCOPE_AGENT); }
; #define XB_SPIN(cond, bar) do { unsigned _sp = 0; while (cond) { __builtin_amdgcn_s_sleep(1); \
;     if ((++_sp & 255u) == 0u) { if (xb_ld(&(bar)[XB_TMO])) break; if (_sp > XB_SPIN_CAP) { atomicAdd(&(bar)[XB_TMO], 1u); break; } } } } while (0)
; #define SEAM(k) do { if (IN(k) && IN((k) + 1)) xcd_barrier(bar); } while (0)
; __device__ __forceinline__ void xcd_barrier(const XcdBarrier& b) {
;     asm volatile("s_waitcnt vmcnt(0)" ::: "memory");
;     __syncthreads();
;     if (threadIdx.x == 0) {
;         unsigned* bar = b.bar;
;         __builtin_amdgcn_s_waitcnt(0);
;         unsigned nloc = b.st[0], nx = b.st[1];
;         if (nloc == 0u) { xcd_barrier_complete(bar, b.x, nloc, nx); b.st[0] = nloc; b.st[1] = nx; }
;         const unsigned old = xb_add(&bar[XB_XSUB(b.x)], 1u);
;         const unsigned gen = old / nloc;
;         if (old + 1u == (gen + 1u) * nloc) {
;             __builtin_amdgcn_fence(__ATOMIC_RELEASE, "agent");
;             asm volatile("s_waitcnt vmcnt(0)" ::: "memory");
;             const unsigned og = xb_add(&bar[XB_TOP], 1u);
;             const unsigned tg = og / nx;
;             if (og + 1u == (tg + 1u) * nx) xb_add(&bar[XB_TOPGEN], 1u);
;             else XB_SPIN(xb_ld(&bar[XB_TOPGEN]) == tg, bar);
;             __builtin_amdgcn_fence(__ATOMIC_ACQUIRE, "agent");
;             xb_add(&bar[XB_XGEN(b.x)], 1u);
;             asm volatile("s_waitcnt vmcnt(0)" ::: "memory");
;         } else {
;             XB_SPIN(xb_ld(&bar[XB_XGEN(b.x)]) == gen, bar);
;             __builtin_amdgcn_fence(__ATOMIC_ACQUIRE, "agent");
;             asm volatile("s_waitcnt vmcnt(0)" ::: "memory");
;         }
;     }
;     __syncthreads();
; }
; __global__ void __launch_bounds__(NWAVES * 64, 2) mega_fwd(Args args) {
;     ...
;     SEAM(10);
;     if (IN(11)) { pg8::Gemm g{ACT, W2d, M, DM, FF, 64, FF, 0, 0, 1, (size_t)256 * 64 * 2, (size_t)(FF / 64) * 256 * 64 * 2}; pg8::StaticOrder S; S.init(M, DM, 1, G, bx);
;         pg8::EpiResid<true> E{nullptr, XB, ss3, 0.5f}; pg8::gemm_phase<pg8::EpiResid<true>, true>(lds, g, S, E); }
.LBB0_1327:
	s_cmp_gt_i32 s85, 11
	s_cselect_b64 s[2:3], -1, 0
	s_and_b64 s[0:1], s[0:1], s[2:3]
	v_readlane_b32 s48, v252, 22
	s_andn2_b64 vcc, exec, s[0:1]
	v_readlane_b32 s49, v252, 23
	s_cbranch_vccnz .LBB0_1381
	s_waitcnt vmcnt(0)
	s_waitcnt vmcnt(0) lgkmcnt(0)
	s_barrier
	s_and_saveexec_b64 s[0:1], s[74:75]
	s_cbranch_execz .LBB0_1380
	s_and_b32 s4, s88, 7
	s_lshl_b32 s4, s4, 3
	s_bfe_u32 s5, s88, 0x30003
	s_or_b32 s4, s4, s5
	s_lshl_b32 s4, s4, 8
	s_add_u32 s6, s66, 0xfd09000
	s_addc_u32 s7, s67, 0
	v_mov_b32_e32 v1, s4
	v_mov_b32_e32 v2, 1
	global_atomic_add v1, v2, s[6:7]
	s_movk_i32 s5, 20
	s_mov_b32 s8, 0

; __device__ __forceinline__ unsigned xb_ld(unsigned* p)              { return __hip_atomic_load(p, __ATOMIC_RELAXED, __HIP_MEMORY_SCOPE_AGENT); }
; __device__ __forceinline__ unsigned xb_add(unsigned* p, unsigned v) { return __hip_atomic_fetch_add(p, v, __ATOMIC_RELAXED, __HIP_MEMORY_SCOPE_AGENT); }
; #define XB_SPIN(cond, bar) do { unsigned _sp = 0; while (cond) { __builtin_amdgcn_s_sleep(1); \
;     if ((++_sp & 255u) == 0u) { if (xb_ld(&(bar)[XB_TMO])) break; if (_sp > XB_SPIN_CAP) { atomicAdd(&(bar)[XB_TMO], 1u); break; } } } } while (0)
; #define SEAM(k) do { if (IN(k) && IN((k) + 1)) xcd_barrier(bar); } while (0)
; __device__ __forceinline__ void xcd_barrier(const XcdBarrier& b) {
;     asm volatile("s_waitcnt vmcnt(0)" ::: "memory");
;     __syncthreads();
;     if (threadIdx.x == 0) {
;         unsigned* bar = b.bar;
;         __builtin_amdgcn_s_waitcnt(0);
;         unsigned nloc = b.st[0], nx = b.st[1];
;         if (nloc == 0u) { xcd_barrier_complete(bar, b.x, nloc, nx); b.st[0] = nloc; b.st[1] = nx; }
;         const unsigned old = xb_add(&bar[XB_XSUB(b.x)], 1u);
;         const unsigned gen = old / nloc;
;         if (old + 1u == (gen + 1u) * nloc) {
;             __builtin_amdgcn_fence(__ATOMIC_RELEASE, "agent");
;             asm volatile("s_waitcnt vmcnt(0)" ::: "memory");
;             const unsigned og = xb_add(&bar[XB_TOP], 1u);
;             const unsigned tg = og / nx;
;             if (og + 1u == (tg + 1u) * nx) xb_add(&bar[XB_TOPGEN], 1u);
;             else XB_SPIN(xb_ld(&bar[XB_TOPGEN]) == tg, bar);
;             __builtin_amdgcn_fence(__ATOMIC_ACQUIRE, "agent");
;             xb_add(&bar[XB_XGEN(b.x)], 1u);
;             asm volatile("s_waitcnt vmcnt(0)" ::: "memory");
;         } else {
;             XB_SPIN(xb_ld(&bar[XB_XGEN(b.x)]) == gen, bar);
;             __builtin_amdgcn_fence(__ATOMIC_ACQUIRE, "agent");
;             asm volatile("s_waitcnt vmcnt(0)" ::: "memory");
;         }
;     }
;     __syncthreads();
; }
; __global__ void __launch_bounds__(NWAVES * 64, 2) mega_fwd(Args args) {
;     ...
;     SEAM(11);
;     if (IN(12)) { pg8::StaticOrder S; S.init(M, DM, 1, G, bx);
;         { pg8::Gemm g{XB, Wpg, M, DM, DM, DM, DM, 0, 0, 1}; pg8::EpiPle2 E{ss3, PTMP, XB, out}; pg8::gemm_phase<pg8::EpiPle2, true>(lds, g, S, E); } }
.LBB0_1428:
	s_cmp_gt_i32 s85, 12
	s_cselect_b64 s[2:3], -1, 0
	s_and_b64 s[0:1], s[0:1], s[2:3]
	s_andn2_b64 vcc, exec, s[0:1]
	s_cbranch_vccnz .LBB0_1482
	s_waitcnt vmcnt(0)
	s_waitcnt vmcnt(0) lgkmcnt(0)
	s_barrier
	s_and_saveexec_b64 s[0:1], s[74:75]
	s_cbranch_execz .LBB0_1481
	s_and_b32 s4, s88, 7
	s_lshl_b32 s4, s4, 3
	s_bfe_u32 s5, s88, 0x30003
	s_or_b32 s4, s4, s5
	s_lshl_b32 s4, s4, 8
	s_add_u32 s6, s66, 0xfd09000
	s_addc_u32 s7, s67, 0
	v_mov_b32_e32 v1, s4
	v_mov_b32_e32 v2, 1
	global_atomic_add v1, v2, s[6:7]
	s_movk_i32 s5, 24
	s_mov_b32 s8, 0
